# v71 + P0 x/weight bf16 stores marked sc1 (write-through: less dirty L2 to flush at barrier 1)
# speedup vs baseline: 1.0051x; 1.0037x over previous
.LBB0_105:
	s_or_b64 exec, exec, s[60:61]
	s_lshl_b32 s51, s51, 14
	s_add_i32 s60, s51, 0
	s_and_b64 vcc, exec, s[34:35]
	v_lshrrev_b32_e32 v181, 3, v162
	v_lshlrev_b32_e32 v162, 3, v162
	s_cbranch_vccnz .LBB0_108
	v_lshlrev_b32_e32 v230, 2, v166
	v_cmp_gt_u32_e32 vcc, s53, v166
	v_mul_u32_u24_e32 v231, 0x84, v167
	v_add3_u32 v230, s60, v230, v231
	s_waitcnt vmcnt(31)
	v_cndmask_b32_e32 v165, 0, v165, vcc
	s_waitcnt vmcnt(30)
	v_cndmask_b32_e32 v163, 0, v163, vcc
	ds_write2_b32 v230, v165, v163 offset1:66
	s_waitcnt vmcnt(29)
	v_cndmask_b32_e32 v163, 0, v164, vcc
	s_waitcnt vmcnt(28)
	v_cndmask_b32_e32 v164, 0, v168, vcc
	ds_write2_b32 v230, v163, v164 offset0:132 offset1:198
	s_waitcnt vmcnt(27)
	v_cndmask_b32_e32 v163, 0, v169, vcc
	s_waitcnt vmcnt(26)
	v_cndmask_b32_e32 v164, 0, v171, vcc
	v_add_u32_e32 v165, 0x400, v230
	ds_write2_b32 v165, v163, v164 offset0:8 offset1:74
	s_waitcnt vmcnt(25)
	v_cndmask_b32_e32 v163, 0, v170, vcc
	s_waitcnt vmcnt(24)
	v_cndmask_b32_e32 v164, 0, v172, vcc
	ds_write2_b32 v165, v163, v164 offset0:140 offset1:206
	s_waitcnt vmcnt(23)
	v_cndmask_b32_e32 v163, 0, v173, vcc
	s_waitcnt vmcnt(22)
	v_cndmask_b32_e32 v164, 0, v175, vcc
	v_add_u32_e32 v165, 0x800, v230
	ds_write2_b32 v165, v163, v164 offset0:16 offset1:82
	s_waitcnt vmcnt(21)
	v_cndmask_b32_e32 v163, 0, v174, vcc
	s_waitcnt vmcnt(20)
	v_cndmask_b32_e32 v164, 0, v176, vcc
	ds_write2_b32 v165, v163, v164 offset0:148 offset1:214
	s_waitcnt vmcnt(19)
	v_cndmask_b32_e32 v163, 0, v177, vcc
	s_waitcnt vmcnt(18)
	v_cndmask_b32_e32 v164, 0, v179, vcc
	v_add_u32_e32 v165, 0xc00, v230
	ds_write2_b32 v165, v163, v164 offset0:24 offset1:90
	s_waitcnt vmcnt(17)
	v_cndmask_b32_e32 v163, 0, v178, vcc
	s_waitcnt vmcnt(16)
	v_cndmask_b32_e32 v164, 0, v180, vcc
	ds_write2_b32 v165, v163, v164 offset0:156 offset1:222
	s_waitcnt vmcnt(15)
	v_cndmask_b32_e32 v163, 0, v189, vcc
	s_waitcnt vmcnt(14)
	v_cndmask_b32_e32 v164, 0, v191, vcc
	v_add_u32_e32 v165, 0x1000, v230
	ds_write2_b32 v165, v163, v164 offset0:32 offset1:98
	s_waitcnt vmcnt(13)
	v_cndmask_b32_e32 v163, 0, v190, vcc
	s_waitcnt vmcnt(12)
	v_cndmask_b32_e32 v164, 0, v192, vcc
	ds_write2_b32 v165, v163, v164 offset0:164 offset1:230
	s_waitcnt vmcnt(11)
	v_cndmask_b32_e32 v163, 0, v193, vcc
	s_waitcnt vmcnt(10)
	v_cndmask_b32_e32 v164, 0, v195, vcc
	v_add_u32_e32 v165, 0x1400, v230
	ds_write2_b32 v165, v163, v164 offset0:40 offset1:106
	s_waitcnt vmcnt(9)
	v_cndmask_b32_e32 v163, 0, v194, vcc
	s_waitcnt vmcnt(8)
	v_cndmask_b32_e32 v164, 0, v196, vcc
	ds_write2_b32 v165, v163, v164 offset0:172 offset1:238
	s_waitcnt vmcnt(7)
	v_cndmask_b32_e32 v163, 0, v206, vcc
	s_waitcnt vmcnt(6)
	v_cndmask_b32_e32 v164, 0, v208, vcc
	v_add_u32_e32 v165, 0x1800, v230
	ds_write2_b32 v165, v163, v164 offset0:48 offset1:114
	s_waitcnt vmcnt(5)
	v_cndmask_b32_e32 v163, 0, v207, vcc
	s_waitcnt vmcnt(4)
	v_cndmask_b32_e32 v164, 0, v209, vcc
	ds_write2_b32 v165, v163, v164 offset0:180 offset1:246
	s_waitcnt vmcnt(3)
	v_cndmask_b32_e32 v163, 0, v210, vcc
	s_waitcnt vmcnt(2)
	v_cndmask_b32_e32 v164, 0, v212, vcc
	v_add_u32_e32 v165, 0x1c00, v230
	ds_write2_b32 v165, v163, v164 offset0:56 offset1:122
	s_waitcnt vmcnt(1)
	v_cndmask_b32_e32 v163, 0, v211, vcc
	s_waitcnt vmcnt(0)
	v_cndmask_b32_e32 v164, 0, v213, vcc
	ds_write2_b32 v165, v163, v164 offset0:188 offset1:254
	v_and_b32_e32 v163, 56, v162
	s_waitcnt lgkmcnt(0)
	v_mul_u32_u24_e32 v164, 0x84, v163
	v_lshlrev_b32_e32 v165, 2, v181
	v_add3_u32 v180, s60, v164, v165
	s_add_u32 s51, s38, s58
	ds_read2_b32 v[164:165], v180 offset1:8
	s_addc_u32 s58, s39, s59
	s_ashr_i32 s53, s52, 31
	ds_read2_b32 v[176:177], v180 offset0:33 offset1:41
	s_lshl_b64 s[34:35], s[52:53], 1
	s_add_u32 s34, s51, s34
	ds_read2_b32 v[178:179], v180 offset0:66 offset1:74
	s_addc_u32 s35, s58, s35
	v_lshlrev_b32_e32 v172, 1, v163
	v_mov_b32_e32 v173, 0
	ds_read2_b32 v[190:191], v180 offset0:99 offset1:107
	v_lshl_add_u64 v[174:175], s[34:35], 0, v[172:173]
	s_waitcnt lgkmcnt(3)
	v_bfe_u32 v163, v164, 16, 1
	s_movk_i32 s34, 0x7fff
	v_add3_u32 v163, v164, v163, s34
	s_waitcnt lgkmcnt(2)
	v_bfe_u32 v164, v176, 16, 1
	ds_read2_b32 v[192:193], v180 offset0:132 offset1:140
	v_lshrrev_b32_e32 v163, 16, v163
	v_add3_u32 v164, v176, v164, s34
	s_mov_b32 s35, 0xffff0000
	ds_read2_b32 v[194:195], v180 offset0:165 offset1:173
	v_and_or_b32 v168, v164, s35, v163
	s_waitcnt lgkmcnt(3)
	v_bfe_u32 v163, v178, 16, 1
	v_add3_u32 v163, v178, v163, s34
	s_waitcnt lgkmcnt(2)
	v_bfe_u32 v164, v190, 16, 1
	ds_read2_b32 v[206:207], v180 offset0:198 offset1:206
	v_lshrrev_b32_e32 v163, 16, v163
	v_add3_u32 v164, v190, v164, s34
	ds_read2_b32 v[208:209], v180 offset0:231 offset1:239
	v_and_or_b32 v169, v164, s35, v163
	s_waitcnt lgkmcnt(3)
	v_bfe_u32 v163, v192, 16, 1
	v_add3_u32 v163, v192, v163, s34
	s_waitcnt lgkmcnt(2)
	v_bfe_u32 v164, v194, 16, 1
	v_lshrrev_b32_e32 v163, 16, v163
	v_add3_u32 v164, v194, v164, s34
	v_and_or_b32 v170, v164, s35, v163
	s_waitcnt lgkmcnt(1)
	v_bfe_u32 v163, v206, 16, 1
	v_add3_u32 v163, v206, v163, s34
	s_waitcnt lgkmcnt(0)
	v_bfe_u32 v164, v208, 16, 1
	v_lshrrev_b32_e32 v163, 16, v163
	v_add3_u32 v164, v208, v164, s34
	v_and_or_b32 v171, v164, s35, v163
	v_bfe_u32 v163, v165, 16, 1
	v_add_lshl_u32 v172, s66, v181, 10
	v_add3_u32 v163, v165, v163, s34
	v_bfe_u32 v164, v177, 16, 1
	v_lshl_add_u64 v[210:211], v[172:173], 1, v[174:175]
	v_lshrrev_b32_e32 v163, 16, v163
	v_add3_u32 v164, v177, v164, s34
	global_store_dwordx4 v[210:211], v[168:171], off sc1
	v_mov_b32_e32 v165, v173
	ds_read2_b32 v[176:177], v180 offset0:16 offset1:24
	v_and_or_b32 v168, v164, s35, v163
	v_bfe_u32 v163, v179, 16, 1
	v_add3_u32 v163, v179, v163, s34
	v_bfe_u32 v164, v191, 16, 1
	v_lshrrev_b32_e32 v163, 16, v163
	v_add3_u32 v164, v191, v164, s34
	v_and_or_b32 v169, v164, s35, v163
	v_bfe_u32 v163, v193, 16, 1
	v_add3_u32 v163, v193, v163, s34
	v_bfe_u32 v164, v195, 16, 1
	v_lshrrev_b32_e32 v163, 16, v163
	v_add3_u32 v164, v195, v164, s34
	v_and_or_b32 v170, v164, s35, v163
	v_bfe_u32 v163, v207, 16, 1
	v_add3_u32 v163, v207, v163, s34
	v_bfe_u32 v164, v209, 16, 1
	v_lshrrev_b32_e32 v163, 16, v163
	v_add3_u32 v164, v209, v164, s34
	v_and_or_b32 v171, v164, s35, v163
	v_add_u32_e32 v164, 0x2000, v172
	v_lshl_add_u64 v[164:165], v[164:165], 1, v[174:175]
	global_store_dwordx4 v[164:165], v[168:171], off sc1
	ds_read2_b32 v[164:165], v180 offset0:49 offset1:57
	ds_read2_b32 v[178:179], v180 offset0:82 offset1:90
	ds_read2_b32 v[190:191], v180 offset0:115 offset1:123
	s_waitcnt lgkmcnt(3)
	v_bfe_u32 v163, v176, 16, 1
	v_add3_u32 v163, v176, v163, s34
	s_waitcnt lgkmcnt(2)
	v_bfe_u32 v168, v164, 16, 1
	ds_read2_b32 v[192:193], v180 offset0:148 offset1:156
	v_lshrrev_b32_e32 v163, 16, v163
	v_add3_u32 v164, v164, v168, s34
	ds_read2_b32 v[194:195], v180 offset0:181 offset1:189
	v_and_or_b32 v168, v164, s35, v163
	s_waitcnt lgkmcnt(3)
	v_bfe_u32 v163, v178, 16, 1
	v_add3_u32 v163, v178, v163, s34
	s_waitcnt lgkmcnt(2)
	v_bfe_u32 v164, v190, 16, 1
	ds_read2_b32 v[206:207], v180 offset0:214 offset1:222
	v_lshrrev_b32_e32 v163, 16, v163
	v_add3_u32 v164, v190, v164, s34
	ds_read2_b32 v[208:209], v180 offset0:247 offset1:255
	v_and_or_b32 v169, v164, s35, v163
	s_waitcnt lgkmcnt(3)
	v_bfe_u32 v163, v192, 16, 1
	v_add3_u32 v163, v192, v163, s34
	s_waitcnt lgkmcnt(2)
	v_bfe_u32 v164, v194, 16, 1
	v_lshrrev_b32_e32 v163, 16, v163
	v_add3_u32 v164, v194, v164, s34
	v_and_or_b32 v170, v164, s35, v163
	s_waitcnt lgkmcnt(1)
	v_bfe_u32 v163, v206, 16, 1
	v_add3_u32 v163, v206, v163, s34
	s_waitcnt lgkmcnt(0)
	v_bfe_u32 v164, v208, 16, 1
	v_lshrrev_b32_e32 v163, 16, v163
	v_add3_u32 v164, v208, v164, s34
	v_and_or_b32 v171, v164, s35, v163
	v_bfe_u32 v163, v177, 16, 1
	v_add_u32_e32 v210, 0x4000, v172
	v_mov_b32_e32 v211, v173
	v_add3_u32 v163, v177, v163, s34
	v_bfe_u32 v164, v165, 16, 1
	v_lshl_add_u64 v[210:211], v[210:211], 1, v[174:175]
	v_lshrrev_b32_e32 v163, 16, v163
	v_add3_u32 v164, v165, v164, s34
	global_store_dwordx4 v[210:211], v[168:171], off sc1
	v_add_u32_e32 v172, 0x6000, v172
	s_nop 0
	v_and_or_b32 v168, v164, s35, v163
	v_bfe_u32 v163, v179, 16, 1
	v_add3_u32 v163, v179, v163, s34
	v_bfe_u32 v164, v191, 16, 1
	v_lshrrev_b32_e32 v163, 16, v163
	v_add3_u32 v164, v191, v164, s34
	v_and_or_b32 v169, v164, s35, v163
	v_bfe_u32 v163, v193, 16, 1
	v_add3_u32 v163, v193, v163, s34
	v_bfe_u32 v164, v195, 16, 1
	v_lshrrev_b32_e32 v163, 16, v163
	v_add3_u32 v164, v195, v164, s34
	v_and_or_b32 v170, v164, s35, v163
	v_bfe_u32 v163, v207, 16, 1
	v_add3_u32 v163, v207, v163, s34
	v_bfe_u32 v164, v209, 16, 1
	v_lshrrev_b32_e32 v163, 16, v163
	v_add3_u32 v164, v209, v164, s34
	v_and_or_b32 v171, v164, s35, v163
	v_lshl_add_u64 v[164:165], v[172:173], 1, v[174:175]
	global_store_dwordx4 v[164:165], v[168:171], off sc1
	s_waitcnt lgkmcnt(0)
	s_and_b64 vcc, exec, s[36:37]
	s_cbranch_vccz .LBB0_109

.LBB0_109:
	s_waitcnt vmcnt(30)
	v_lshlrev_b32_e32 v163, 2, v166
	v_cmp_gt_u32_e32 vcc, s65, v166
	v_mul_u32_u24_e32 v165, 0x84, v167
	v_add3_u32 v163, s60, v163, v165
	s_waitcnt vmcnt(29)
	v_cndmask_b32_e32 v164, 0, v197, vcc
	v_cndmask_b32_e32 v165, 0, v188, vcc
	ds_write2_b32 v163, v164, v165 offset1:66
	v_cndmask_b32_e32 v164, 0, v187, vcc
	s_waitcnt vmcnt(28)
	v_cndmask_b32_e32 v165, 0, v186, vcc
	ds_write2_b32 v163, v164, v165 offset0:132 offset1:198
	s_waitcnt vmcnt(27)
	v_cndmask_b32_e32 v164, 0, v185, vcc
	s_waitcnt vmcnt(26)
	v_cndmask_b32_e32 v165, 0, v184, vcc
	v_add_u32_e32 v168, 0x400, v163
	ds_write2_b32 v168, v164, v165 offset0:8 offset1:74
	s_waitcnt vmcnt(25)
	v_cndmask_b32_e32 v164, 0, v183, vcc
	s_waitcnt vmcnt(24)
	v_cndmask_b32_e32 v165, 0, v182, vcc
	ds_write2_b32 v168, v164, v165 offset0:140 offset1:206
	s_waitcnt vmcnt(23)
	v_cndmask_b32_e32 v164, 0, v205, vcc
	s_waitcnt vmcnt(22)
	v_cndmask_b32_e32 v165, 0, v204, vcc
	v_add_u32_e32 v168, 0x800, v163
	ds_write2_b32 v168, v164, v165 offset0:16 offset1:82
	s_waitcnt vmcnt(21)
	v_cndmask_b32_e32 v164, 0, v203, vcc
	s_waitcnt vmcnt(20)
	v_cndmask_b32_e32 v165, 0, v202, vcc
	ds_write2_b32 v168, v164, v165 offset0:148 offset1:214
	s_waitcnt vmcnt(19)
	v_cndmask_b32_e32 v164, 0, v201, vcc
	s_waitcnt vmcnt(18)
	v_cndmask_b32_e32 v165, 0, v200, vcc
	v_add_u32_e32 v168, 0xc00, v163
	ds_write2_b32 v168, v164, v165 offset0:24 offset1:90
	s_waitcnt vmcnt(17)
	v_cndmask_b32_e32 v164, 0, v199, vcc
	s_waitcnt vmcnt(16)
	v_cndmask_b32_e32 v165, 0, v198, vcc
	ds_write2_b32 v168, v164, v165 offset0:156 offset1:222
	s_waitcnt vmcnt(15)
	v_cndmask_b32_e32 v164, 0, v221, vcc
	s_waitcnt vmcnt(14)
	v_cndmask_b32_e32 v165, 0, v220, vcc
	v_add_u32_e32 v168, 0x1000, v163
	ds_write2_b32 v168, v164, v165 offset0:32 offset1:98
	s_waitcnt vmcnt(13)
	v_cndmask_b32_e32 v164, 0, v219, vcc
	s_waitcnt vmcnt(12)
	v_cndmask_b32_e32 v165, 0, v218, vcc
	ds_write2_b32 v168, v164, v165 offset0:164 offset1:230
	s_waitcnt vmcnt(11)
	v_cndmask_b32_e32 v164, 0, v217, vcc
	s_waitcnt vmcnt(10)
	v_cndmask_b32_e32 v165, 0, v216, vcc
	v_add_u32_e32 v168, 0x1400, v163
	ds_write2_b32 v168, v164, v165 offset0:40 offset1:106
	s_waitcnt vmcnt(9)
	v_cndmask_b32_e32 v164, 0, v215, vcc
	s_waitcnt vmcnt(8)
	v_cndmask_b32_e32 v165, 0, v214, vcc
	ds_write2_b32 v168, v164, v165 offset0:172 offset1:238
	s_waitcnt vmcnt(7)
	v_cndmask_b32_e32 v164, 0, v223, vcc
	s_waitcnt vmcnt(6)
	v_cndmask_b32_e32 v165, 0, v222, vcc
	v_add_u32_e32 v168, 0x1800, v163
	ds_write2_b32 v168, v164, v165 offset0:48 offset1:114
	s_waitcnt vmcnt(5)
	v_cndmask_b32_e32 v164, 0, v224, vcc
	s_waitcnt vmcnt(4)
	v_cndmask_b32_e32 v165, 0, v225, vcc
	ds_write2_b32 v168, v164, v165 offset0:180 offset1:246
	s_waitcnt vmcnt(3)
	v_cndmask_b32_e32 v164, 0, v226, vcc
	s_waitcnt vmcnt(2)
	v_cndmask_b32_e32 v165, 0, v228, vcc
	v_add_u32_e32 v163, 0x1c00, v163
	ds_write2_b32 v163, v164, v165 offset0:56 offset1:122
	s_waitcnt vmcnt(1)
	v_cndmask_b32_e32 v164, 0, v227, vcc
	s_waitcnt vmcnt(0)
	v_cndmask_b32_e32 v165, 0, v229, vcc
	ds_write2_b32 v163, v164, v165 offset0:188 offset1:254
	v_and_b32_e32 v163, 56, v162
	s_waitcnt lgkmcnt(0)
	v_mul_u32_u24_e32 v164, 0x84, v163
	v_lshlrev_b32_e32 v165, 2, v181
	v_add3_u32 v180, s60, v164, v165
	s_add_u32 s36, s38, s54
	ds_read2_b32 v[164:165], v180 offset1:8
	s_addc_u32 s37, s39, s55
	s_ashr_i32 s51, s50, 31
	ds_read2_b32 v[176:177], v180 offset0:33 offset1:41
	s_lshl_b64 s[34:35], s[50:51], 1
	s_add_u32 s34, s36, s34
	ds_read2_b32 v[178:179], v180 offset0:66 offset1:74
	s_addc_u32 s35, s37, s35
	v_lshlrev_b32_e32 v172, 1, v163
	v_mov_b32_e32 v173, 0
	ds_read2_b32 v[182:183], v180 offset0:99 offset1:107
	v_lshl_add_u64 v[174:175], s[34:35], 0, v[172:173]
	s_waitcnt lgkmcnt(3)
	v_bfe_u32 v163, v164, 16, 1
	s_movk_i32 s34, 0x7fff
	v_add3_u32 v163, v164, v163, s34
	s_waitcnt lgkmcnt(2)
	v_bfe_u32 v164, v176, 16, 1
	ds_read2_b32 v[184:185], v180 offset0:132 offset1:140
	v_lshrrev_b32_e32 v163, 16, v163
	v_add3_u32 v164, v176, v164, s34
	s_mov_b32 s35, 0xffff0000
	ds_read2_b32 v[186:187], v180 offset0:165 offset1:173
	v_and_or_b32 v168, v164, s35, v163
	s_waitcnt lgkmcnt(3)
	v_bfe_u32 v163, v178, 16, 1
	v_add3_u32 v163, v178, v163, s34
	s_waitcnt lgkmcnt(2)
	v_bfe_u32 v164, v182, 16, 1
	ds_read2_b32 v[188:189], v180 offset0:198 offset1:206
	v_lshrrev_b32_e32 v163, 16, v163
	v_add3_u32 v164, v182, v164, s34
	ds_read2_b32 v[190:191], v180 offset0:231 offset1:239
	v_and_or_b32 v169, v164, s35, v163
	s_waitcnt lgkmcnt(3)
	v_bfe_u32 v163, v184, 16, 1
	v_add3_u32 v163, v184, v163, s34
	s_waitcnt lgkmcnt(2)
	v_bfe_u32 v164, v186, 16, 1
	v_lshrrev_b32_e32 v163, 16, v163
	v_add3_u32 v164, v186, v164, s34
	v_and_or_b32 v170, v164, s35, v163
	s_waitcnt lgkmcnt(1)
	v_bfe_u32 v163, v188, 16, 1
	v_add3_u32 v163, v188, v163, s34
	s_waitcnt lgkmcnt(0)
	v_bfe_u32 v164, v190, 16, 1
	v_lshrrev_b32_e32 v163, 16, v163
	v_add3_u32 v164, v190, v164, s34
	v_and_or_b32 v171, v164, s35, v163
	v_bfe_u32 v163, v165, 16, 1
	v_add_lshl_u32 v172, s64, v181, 10
	v_add3_u32 v163, v165, v163, s34
	v_bfe_u32 v164, v177, 16, 1
	v_lshl_add_u64 v[192:193], v[172:173], 1, v[174:175]
	v_lshrrev_b32_e32 v163, 16, v163
	v_add3_u32 v164, v177, v164, s34
	global_store_dwordx4 v[192:193], v[168:171], off sc1
	v_mov_b32_e32 v165, v173
	ds_read2_b32 v[176:177], v180 offset0:16 offset1:24
	v_and_or_b32 v168, v164, s35, v163
	v_bfe_u32 v163, v179, 16, 1
	v_add3_u32 v163, v179, v163, s34
	v_bfe_u32 v164, v183, 16, 1
	v_lshrrev_b32_e32 v163, 16, v163
	v_add3_u32 v164, v183, v164, s34
	v_and_or_b32 v169, v164, s35, v163
	v_bfe_u32 v163, v185, 16, 1
	v_add3_u32 v163, v185, v163, s34
	v_bfe_u32 v164, v187, 16, 1
	v_lshrrev_b32_e32 v163, 16, v163
	v_add3_u32 v164, v187, v164, s34
	v_and_or_b32 v170, v164, s35, v163
	v_bfe_u32 v163, v189, 16, 1
	v_add3_u32 v163, v189, v163, s34
	v_bfe_u32 v164, v191, 16, 1
	v_lshrrev_b32_e32 v163, 16, v163
	v_add3_u32 v164, v191, v164, s34
	v_and_or_b32 v171, v164, s35, v163
	v_add_u32_e32 v164, 0x2000, v172
	v_lshl_add_u64 v[164:165], v[164:165], 1, v[174:175]
	global_store_dwordx4 v[164:165], v[168:171], off sc1
	ds_read2_b32 v[164:165], v180 offset0:49 offset1:57
	ds_read2_b32 v[178:179], v180 offset0:82 offset1:90
	ds_read2_b32 v[182:183], v180 offset0:115 offset1:123
	s_waitcnt lgkmcnt(3)
	v_bfe_u32 v163, v176, 16, 1
	v_add3_u32 v163, v176, v163, s34
	s_waitcnt lgkmcnt(2)
	v_bfe_u32 v168, v164, 16, 1
	ds_read2_b32 v[184:185], v180 offset0:148 offset1:156
	v_lshrrev_b32_e32 v163, 16, v163
	v_add3_u32 v164, v164, v168, s34
	ds_read2_b32 v[186:187], v180 offset0:181 offset1:189
	v_and_or_b32 v168, v164, s35, v163
	s_waitcnt lgkmcnt(3)
	v_bfe_u32 v163, v178, 16, 1
	v_add3_u32 v163, v178, v163, s34
	s_waitcnt lgkmcnt(2)
	v_bfe_u32 v164, v182, 16, 1
	ds_read2_b32 v[188:189], v180 offset0:214 offset1:222
	v_lshrrev_b32_e32 v163, 16, v163
	v_add3_u32 v164, v182, v164, s34
	ds_read2_b32 v[190:191], v180 offset0:247 offset1:255
	v_and_or_b32 v169, v164, s35, v163
	s_waitcnt lgkmcnt(3)
	v_bfe_u32 v163, v184, 16, 1
	v_add3_u32 v163, v184, v163, s34
	s_waitcnt lgkmcnt(2)
	v_bfe_u32 v164, v186, 16, 1
	v_lshrrev_b32_e32 v163, 16, v163
	v_add3_u32 v164, v186, v164, s34
	v_and_or_b32 v170, v164, s35, v163
	s_waitcnt lgkmcnt(1)
	v_bfe_u32 v163, v188, 16, 1
	v_add3_u32 v163, v188, v163, s34
	s_waitcnt lgkmcnt(0)
	v_bfe_u32 v164, v190, 16, 1
	v_lshrrev_b32_e32 v163, 16, v163
	v_add3_u32 v164, v190, v164, s34
	v_and_or_b32 v171, v164, s35, v163
	v_bfe_u32 v163, v177, 16, 1
	v_add_u32_e32 v192, 0x4000, v172
	v_mov_b32_e32 v193, v173
	v_add3_u32 v163, v177, v163, s34
	v_bfe_u32 v164, v165, 16, 1
	v_lshl_add_u64 v[192:193], v[192:193], 1, v[174:175]
	v_lshrrev_b32_e32 v163, 16, v163
	v_add3_u32 v164, v165, v164, s34
	global_store_dwordx4 v[192:193], v[168:171], off sc1
	v_add_u32_e32 v172, 0x6000, v172
	s_nop 0
	v_and_or_b32 v168, v164, s35, v163
	v_bfe_u32 v163, v179, 16, 1
	v_add3_u32 v163, v179, v163, s34
	v_bfe_u32 v164, v183, 16, 1
	v_lshrrev_b32_e32 v163, 16, v163
	v_add3_u32 v164, v183, v164, s34
	v_and_or_b32 v169, v164, s35, v163
	v_bfe_u32 v163, v185, 16, 1
	v_add3_u32 v163, v185, v163, s34
	v_bfe_u32 v164, v187, 16, 1
	v_lshrrev_b32_e32 v163, 16, v163
	v_add3_u32 v164, v187, v164, s34
	v_and_or_b32 v170, v164, s35, v163
	v_bfe_u32 v163, v189, 16, 1
	v_add3_u32 v163, v189, v163, s34
	v_bfe_u32 v164, v191, 16, 1
	v_lshrrev_b32_e32 v163, 16, v163
	v_add3_u32 v164, v191, v164, s34
	v_and_or_b32 v171, v164, s35, v163
	v_lshl_add_u64 v[164:165], v[172:173], 1, v[174:175]
	global_store_dwordx4 v[164:165], v[168:171], off sc1
	s_waitcnt lgkmcnt(0)
	s_lshl_b32 s34, s56, 4
	s_add_i32 s33, s33, s34
	s_cmpk_gt_i32 s33, 0xc7f
	s_cbranch_scc1 .LBB0_130

.LBB0_113:
	s_waitcnt vmcnt(16)
	v_add_u32_e32 v180, s36, v167
	s_add_u32 s54, s38, s54
	v_sub_u32_e64 v162, s51, 1 clamp
	v_cmp_gt_u32_e32 vcc, s51, v166
	v_mad_i64_i32 v[182:183], s[68:69], v180, s37, 0
	s_addc_u32 s55, s39, s55
	v_cndmask_b32_e32 v162, v162, v166, vcc
	v_lshl_add_u64 v[182:183], v[182:183], 2, s[52:53]
	s_ashr_i32 s51, s50, 31
	v_lshl_add_u64 v[182:183], s[50:51], 2, v[182:183]
	v_lshlrev_b32_e32 v162, 2, v162
	v_lshl_add_u64 v[182:183], v[182:183], 0, v[162:163]
	s_lshl_b32 s34, s37, 3
	v_lshl_add_u64 v[184:185], v[182:183], 0, s[34:35]
	s_lshl_b32 s34, s37, 4
	v_lshl_add_u64 v[186:187], v[182:183], 0, s[34:35]
	s_mul_i32 s34, s37, 24
	s_waitcnt vmcnt(15)
	v_lshl_add_u64 v[188:189], v[182:183], 0, s[34:35]
	s_lshl_b32 s34, s37, 5
	s_waitcnt vmcnt(13)
	v_lshl_add_u64 v[190:191], v[182:183], 0, s[34:35]
	s_mul_i32 s34, s37, 40
	s_waitcnt vmcnt(11)
	v_lshl_add_u64 v[192:193], v[182:183], 0, s[34:35]
	s_mul_i32 s34, s37, 48
	s_waitcnt vmcnt(9)
	v_lshl_add_u64 v[194:195], v[182:183], 0, s[34:35]
	s_mul_i32 s34, s37, 56
	s_waitcnt vmcnt(8)
	v_lshl_add_u64 v[196:197], v[182:183], 0, s[34:35]
	s_lshl_b32 s34, s37, 6
	global_load_dword v162, v[182:183], off
	global_load_dword v180, v[184:185], off
	global_load_dword v200, v[186:187], off
	global_load_dword v201, v[188:189], off
	global_load_dword v202, v[190:191], off
	global_load_dword v203, v[192:193], off
	global_load_dword v204, v[194:195], off
	global_load_dword v205, v[196:197], off
	v_lshl_add_u64 v[184:185], v[182:183], 0, s[34:35]
	s_mul_i32 s34, s37, 0x48
	v_lshl_add_u64 v[186:187], v[182:183], 0, s[34:35]
	s_mul_i32 s34, s37, 0x50
	v_lshl_add_u64 v[188:189], v[182:183], 0, s[34:35]
	s_mul_i32 s34, s37, 0x58
	v_lshl_add_u64 v[190:191], v[182:183], 0, s[34:35]
	s_mul_i32 s34, s37, 0x60
	v_lshl_add_u64 v[192:193], v[182:183], 0, s[34:35]
	s_mul_i32 s34, s37, 0x68
	v_lshl_add_u64 v[194:195], v[182:183], 0, s[34:35]
	s_mul_i32 s34, s37, 0x70
	v_lshl_add_u64 v[196:197], v[182:183], 0, s[34:35]
	s_mul_i32 s34, s37, 0x78
	v_lshl_add_u64 v[198:199], v[182:183], 0, s[34:35]
	s_lshl_b32 s34, s37, 7
	global_load_dword v206, v[184:185], off
	global_load_dword v207, v[186:187], off
	global_load_dword v208, v[188:189], off
	global_load_dword v209, v[190:191], off
	global_load_dword v210, v[192:193], off
	global_load_dword v211, v[194:195], off
	global_load_dword v212, v[196:197], off
	global_load_dword v213, v[198:199], off
	v_lshl_add_u64 v[184:185], v[182:183], 0, s[34:35]
	s_mul_i32 s34, s37, 0x88
	v_lshl_add_u64 v[186:187], v[182:183], 0, s[34:35]
	s_mul_i32 s34, s37, 0x90
	v_lshl_add_u64 v[188:189], v[182:183], 0, s[34:35]
	s_mul_i32 s34, s37, 0x98
	v_lshl_add_u64 v[190:191], v[182:183], 0, s[34:35]
	s_mul_i32 s34, s37, 0xa0
	v_lshl_add_u64 v[192:193], v[182:183], 0, s[34:35]
	s_mul_i32 s34, s37, 0xa8
	v_lshl_add_u64 v[194:195], v[182:183], 0, s[34:35]
	s_mul_i32 s34, s37, 0xb0
	v_lshl_add_u64 v[196:197], v[182:183], 0, s[34:35]
	s_mul_i32 s34, s37, 0xb8
	v_lshl_add_u64 v[198:199], v[182:183], 0, s[34:35]
	s_mul_i32 s34, s37, 0xc0
	global_load_dword v214, v[184:185], off
	global_load_dword v215, v[186:187], off
	global_load_dword v216, v[188:189], off
	global_load_dword v217, v[190:191], off
	global_load_dword v218, v[192:193], off
	global_load_dword v219, v[194:195], off
	s_nop 0
	global_load_dword v196, v[196:197], off
	s_nop 0
	global_load_dword v197, v[198:199], off
	v_lshl_add_u64 v[184:185], v[182:183], 0, s[34:35]
	s_mul_i32 s34, s37, 0xc8
	v_lshl_add_u64 v[186:187], v[182:183], 0, s[34:35]
	s_mul_i32 s34, s37, 0xd0
	v_lshl_add_u64 v[188:189], v[182:183], 0, s[34:35]
	s_mul_i32 s34, s37, 0xd8
	v_lshl_add_u64 v[190:191], v[182:183], 0, s[34:35]
	s_mul_i32 s34, s37, 0xe0
	v_lshl_add_u64 v[192:193], v[182:183], 0, s[34:35]
	s_mul_i32 s34, s37, 0xe8
	v_lshl_add_u64 v[194:195], v[182:183], 0, s[34:35]
	s_mul_i32 s34, s37, 0xf0
	global_load_dword v198, v[184:185], off
	s_nop 0
	global_load_dword v186, v[186:187], off
	s_nop 0
	global_load_dword v187, v[188:189], off
	s_nop 0
	global_load_dword v188, v[190:191], off
	global_load_dword v189, v[192:193], off
	s_nop 0
	global_load_dword v190, v[194:195], off
	v_lshl_add_u64 v[184:185], v[182:183], 0, s[34:35]
	s_mul_i32 s34, s37, 0xf8
	v_lshl_add_u64 v[182:183], v[182:183], 0, s[34:35]
	global_load_dword v184, v[184:185], off
	s_nop 0
	global_load_dword v182, v[182:183], off
	s_ashr_i32 s37, s36, 31
	s_lshl_b64 s[36:37], s[36:37], 1
	s_add_u32 s36, s54, s36
	s_addc_u32 s37, s55, s37
	s_add_i32 s58, s58, s59
	s_add_i32 s60, s60, s61
	s_waitcnt vmcnt(31)
	v_cndmask_b32_e32 v162, 0, v162, vcc
	s_waitcnt vmcnt(30)
	v_cndmask_b32_e32 v180, 0, v180, vcc
	ds_write2_b32 v172, v162, v180 offset1:66
	s_waitcnt vmcnt(29)
	v_cndmask_b32_e32 v162, 0, v200, vcc
	s_waitcnt vmcnt(28)
	v_cndmask_b32_e32 v180, 0, v201, vcc
	ds_write2_b32 v172, v162, v180 offset0:132 offset1:198
	s_waitcnt vmcnt(27)
	v_cndmask_b32_e32 v162, 0, v202, vcc
	s_waitcnt vmcnt(26)
	v_cndmask_b32_e32 v180, 0, v203, vcc
	ds_write2_b32 v173, v162, v180 offset0:8 offset1:74
	s_waitcnt vmcnt(25)
	v_cndmask_b32_e32 v162, 0, v204, vcc
	s_waitcnt vmcnt(24)
	v_cndmask_b32_e32 v180, 0, v205, vcc
	ds_write2_b32 v173, v162, v180 offset0:140 offset1:206
	s_waitcnt vmcnt(23)
	v_cndmask_b32_e32 v162, 0, v206, vcc
	s_waitcnt vmcnt(22)
	v_cndmask_b32_e32 v180, 0, v207, vcc
	ds_write2_b32 v174, v162, v180 offset0:16 offset1:82
	s_waitcnt vmcnt(21)
	v_cndmask_b32_e32 v162, 0, v208, vcc
	s_waitcnt vmcnt(20)
	v_cndmask_b32_e32 v180, 0, v209, vcc
	ds_write2_b32 v174, v162, v180 offset0:148 offset1:214
	s_waitcnt vmcnt(19)
	v_cndmask_b32_e32 v162, 0, v210, vcc
	s_waitcnt vmcnt(18)
	v_cndmask_b32_e32 v180, 0, v211, vcc
	ds_write2_b32 v175, v162, v180 offset0:24 offset1:90
	s_waitcnt vmcnt(17)
	v_cndmask_b32_e32 v162, 0, v212, vcc
	s_waitcnt vmcnt(16)
	v_cndmask_b32_e32 v180, 0, v213, vcc
	ds_write2_b32 v175, v162, v180 offset0:156 offset1:222
	s_waitcnt vmcnt(15)
	v_cndmask_b32_e32 v162, 0, v214, vcc
	s_waitcnt vmcnt(14)
	v_cndmask_b32_e32 v180, 0, v215, vcc
	ds_write2_b32 v176, v162, v180 offset0:32 offset1:98
	s_waitcnt vmcnt(13)
	v_cndmask_b32_e32 v162, 0, v216, vcc
	s_waitcnt vmcnt(12)
	v_cndmask_b32_e32 v180, 0, v217, vcc
	ds_write2_b32 v176, v162, v180 offset0:164 offset1:230
	s_waitcnt vmcnt(11)
	v_cndmask_b32_e32 v162, 0, v218, vcc
	s_waitcnt vmcnt(10)
	v_cndmask_b32_e32 v180, 0, v219, vcc
	ds_write2_b32 v177, v162, v180 offset0:40 offset1:106
	s_waitcnt vmcnt(9)
	v_cndmask_b32_e32 v162, 0, v196, vcc
	s_waitcnt vmcnt(8)
	v_cndmask_b32_e32 v180, 0, v197, vcc
	ds_write2_b32 v177, v162, v180 offset0:172 offset1:238
	s_waitcnt vmcnt(7)
	v_cndmask_b32_e32 v162, 0, v198, vcc
	s_waitcnt vmcnt(6)
	v_cndmask_b32_e32 v180, 0, v186, vcc
	ds_write2_b32 v178, v162, v180 offset0:48 offset1:114
	s_waitcnt vmcnt(5)
	v_cndmask_b32_e32 v162, 0, v187, vcc
	s_waitcnt vmcnt(4)
	v_cndmask_b32_e32 v180, 0, v188, vcc
	ds_write2_b32 v178, v162, v180 offset0:180 offset1:246
	s_waitcnt vmcnt(3)
	v_cndmask_b32_e32 v162, 0, v189, vcc
	s_waitcnt vmcnt(2)
	v_cndmask_b32_e32 v180, 0, v190, vcc
	ds_write2_b32 v179, v162, v180 offset0:56 offset1:122
	s_waitcnt vmcnt(1)
	v_cndmask_b32_e32 v162, 0, v184, vcc
	s_waitcnt vmcnt(0)
	v_cndmask_b32_e32 v180, 0, v182, vcc
	ds_write2_b32 v179, v162, v180 offset0:188 offset1:254
	s_waitcnt lgkmcnt(0)
	ds_read2_b32 v[186:187], v168 offset1:8
	ds_read2_b32 v[190:191], v168 offset0:33 offset1:41
	ds_read2_b32 v[192:193], v168 offset0:66 offset1:74
	ds_read2_b32 v[194:195], v168 offset0:99 offset1:107
	ds_read2_b32 v[196:197], v168 offset0:132 offset1:140
	s_waitcnt lgkmcnt(4)
	v_bfe_u32 v162, v186, 16, 1
	v_add3_u32 v162, v186, v162, s64
	s_waitcnt lgkmcnt(3)
	v_bfe_u32 v180, v190, 16, 1
	v_lshrrev_b32_e32 v162, 16, v162
	v_add3_u32 v180, v190, v180, s64
	ds_read2_b32 v[198:199], v168 offset0:165 offset1:173
	v_and_or_b32 v182, v180, s65, v162
	s_waitcnt lgkmcnt(3)
	v_bfe_u32 v162, v192, 16, 1
	v_add3_u32 v162, v192, v162, s64
	s_waitcnt lgkmcnt(2)
	v_bfe_u32 v180, v194, 16, 1
	ds_read2_b32 v[200:201], v168 offset0:198 offset1:206
	v_lshrrev_b32_e32 v162, 16, v162
	v_add3_u32 v180, v194, v180, s64
	ds_read2_b32 v[202:203], v168 offset0:231 offset1:239
	v_and_or_b32 v183, v180, s65, v162
	s_waitcnt lgkmcnt(3)
	v_bfe_u32 v162, v196, 16, 1
	v_add3_u32 v162, v196, v162, s64
	s_waitcnt lgkmcnt(2)
	v_bfe_u32 v180, v198, 16, 1
	v_lshrrev_b32_e32 v162, 16, v162
	v_add3_u32 v180, v198, v180, s64
	v_and_or_b32 v184, v180, s65, v162
	s_waitcnt lgkmcnt(1)
	v_bfe_u32 v162, v200, 16, 1
	v_add3_u32 v162, v200, v162, s64
	s_waitcnt lgkmcnt(0)
	v_bfe_u32 v180, v202, 16, 1
	v_lshrrev_b32_e32 v162, 16, v162
	v_add3_u32 v180, v202, v180, s64
	v_lshl_add_u64 v[188:189], s[36:37], 0, v[164:165]
	v_and_or_b32 v185, v180, s65, v162
	v_add_lshl_u32 v162, s66, v181, 11
	v_lshl_add_u64 v[204:205], v[188:189], 0, v[162:163]
	v_bfe_u32 v162, v187, 16, 1
	v_add3_u32 v162, v187, v162, s64
	v_bfe_u32 v180, v191, 16, 1
	v_lshrrev_b32_e32 v162, 16, v162
	v_add3_u32 v180, v191, v180, s64
	global_store_dwordx4 v[204:205], v[182:185], off sc1
	ds_read2_b32 v[186:187], v168 offset0:16 offset1:24
	v_readlane_b32 s36, v254, 11
	v_and_or_b32 v182, v180, s65, v162
	v_bfe_u32 v162, v193, 16, 1
	v_add3_u32 v162, v193, v162, s64
	v_bfe_u32 v180, v195, 16, 1
	v_lshrrev_b32_e32 v162, 16, v162
	v_add3_u32 v180, v195, v180, s64
	v_and_or_b32 v183, v180, s65, v162
	v_bfe_u32 v162, v197, 16, 1
	v_add3_u32 v162, v197, v162, s64
	v_bfe_u32 v180, v199, 16, 1
	v_lshrrev_b32_e32 v162, 16, v162
	v_add3_u32 v180, v199, v180, s64
	v_and_or_b32 v184, v180, s65, v162
	v_bfe_u32 v162, v201, 16, 1
	v_add3_u32 v162, v201, v162, s64
	v_bfe_u32 v180, v203, 16, 1
	v_lshrrev_b32_e32 v162, 16, v162
	v_add3_u32 v180, v203, v180, s64
	v_and_or_b32 v185, v180, s65, v162
	v_add_lshl_u32 v162, s66, v169, 11
	v_lshl_add_u64 v[190:191], v[188:189], 0, v[162:163]
	global_store_dwordx4 v[190:191], v[182:185], off sc1
	ds_read2_b32 v[190:191], v168 offset0:49 offset1:57
	ds_read2_b32 v[192:193], v168 offset0:82 offset1:90
	ds_read2_b32 v[194:195], v168 offset0:115 offset1:123
	s_waitcnt lgkmcnt(3)
	v_bfe_u32 v162, v186, 16, 1
	v_add3_u32 v162, v186, v162, s64
	s_waitcnt lgkmcnt(2)
	v_bfe_u32 v180, v190, 16, 1
	ds_read2_b32 v[196:197], v168 offset0:148 offset1:156
	v_lshrrev_b32_e32 v162, 16, v162
	v_add3_u32 v180, v190, v180, s64
	ds_read2_b32 v[198:199], v168 offset0:181 offset1:189
	v_and_or_b32 v182, v180, s65, v162
	s_waitcnt lgkmcnt(3)
	v_bfe_u32 v162, v192, 16, 1
	v_add3_u32 v162, v192, v162, s64
	s_waitcnt lgkmcnt(2)
	v_bfe_u32 v180, v194, 16, 1
	ds_read2_b32 v[200:201], v168 offset0:214 offset1:222
	v_lshrrev_b32_e32 v162, 16, v162
	v_add3_u32 v180, v194, v180, s64
	ds_read2_b32 v[202:203], v168 offset0:247 offset1:255
	v_and_or_b32 v183, v180, s65, v162
	s_waitcnt lgkmcnt(3)
	v_bfe_u32 v162, v196, 16, 1
	v_add3_u32 v162, v196, v162, s64
	s_waitcnt lgkmcnt(2)
	v_bfe_u32 v180, v198, 16, 1
	v_lshrrev_b32_e32 v162, 16, v162
	v_add3_u32 v180, v198, v180, s64
	v_and_or_b32 v184, v180, s65, v162
	s_waitcnt lgkmcnt(1)
	v_bfe_u32 v162, v200, 16, 1
	v_add3_u32 v162, v200, v162, s64
	s_waitcnt lgkmcnt(0)
	v_bfe_u32 v180, v202, 16, 1
	v_lshrrev_b32_e32 v162, 16, v162
	v_add3_u32 v180, v202, v180, s64
	v_and_or_b32 v185, v180, s65, v162
	v_add_lshl_u32 v162, s66, v170, 11
	v_lshl_add_u64 v[204:205], v[188:189], 0, v[162:163]
	v_bfe_u32 v162, v187, 16, 1
	v_add3_u32 v162, v187, v162, s64
	v_bfe_u32 v180, v191, 16, 1
	v_lshrrev_b32_e32 v162, 16, v162
	v_add3_u32 v180, v191, v180, s64
	global_store_dwordx4 v[204:205], v[182:185], off sc1
	s_add_i32 s33, s33, s36
	s_cmpk_gt_i32 s33, 0xc7f
	v_and_or_b32 v182, v180, s65, v162
	v_bfe_u32 v162, v193, 16, 1
	v_add3_u32 v162, v193, v162, s64
	v_bfe_u32 v180, v195, 16, 1
	v_lshrrev_b32_e32 v162, 16, v162
	v_add3_u32 v180, v195, v180, s64
	v_and_or_b32 v183, v180, s65, v162
	v_bfe_u32 v162, v197, 16, 1
	v_add3_u32 v162, v197, v162, s64
	v_bfe_u32 v180, v199, 16, 1
	v_lshrrev_b32_e32 v162, 16, v162
	v_add3_u32 v180, v199, v180, s64
	v_and_or_b32 v184, v180, s65, v162
	v_bfe_u32 v162, v201, 16, 1
	v_add3_u32 v162, v201, v162, s64
	v_bfe_u32 v180, v203, 16, 1
	v_lshrrev_b32_e32 v162, 16, v162
	v_add3_u32 v180, v203, v180, s64
	v_and_or_b32 v185, v180, s65, v162
	v_add_lshl_u32 v162, s66, v171, 11
	v_lshl_add_u64 v[186:187], v[188:189], 0, v[162:163]
	global_store_dwordx4 v[186:187], v[182:185], off sc1
	s_waitcnt lgkmcnt(0)
	v_readlane_b32 s37, v254, 12
	s_cbranch_scc1 .LBB0_130

.LBB0_130:
	s_add_u32 s34, s38, 0x1000000
	s_addc_u32 s35, s39, 0
	s_and_saveexec_b64 s[36:37], s[0:1]
	s_cbranch_execz .LBB0_146
	s_waitcnt vmcnt(1)
	v_bfe_u32 v162, v124, 16, 1
	s_movk_i32 s0, 0x7fff
	v_add3_u32 v124, v124, v162, s0
	v_bfe_u32 v162, v125, 16, 1
	v_lshrrev_b32_e32 v124, 16, v124
	v_add3_u32 v125, v125, v162, s0
	s_mov_b32 s1, 0xffff0000
	v_and_or_b32 v124, v125, s1, v124
	v_bfe_u32 v125, v126, 16, 1
	v_add3_u32 v125, v126, v125, s0
	v_bfe_u32 v126, v127, 16, 1
	v_lshrrev_b32_e32 v125, 16, v125
	v_add3_u32 v126, v127, v126, s0
	v_and_or_b32 v125, v126, s1, v125
	s_waitcnt vmcnt(0)
	v_bfe_u32 v126, v120, 16, 1
	v_add3_u32 v120, v120, v126, s0
	v_bfe_u32 v126, v121, 16, 1
	v_lshrrev_b32_e32 v120, 16, v120
	v_add3_u32 v121, v121, v126, s0
	v_and_or_b32 v126, v121, s1, v120
	v_bfe_u32 v120, v122, 16, 1
	v_add3_u32 v120, v122, v120, s0
	v_bfe_u32 v121, v123, 16, 1
	v_lshrrev_b32_e32 v120, 16, v120
	v_add3_u32 v121, v123, v121, s0
	v_and_or_b32 v127, v121, s1, v120
	v_lshl_add_u64 v[120:121], v[130:131], 4, s[34:35]
	global_store_dwordx4 v[120:121], v[124:127], off sc1
	s_or_b64 exec, exec, s[36:37]
	s_and_saveexec_b64 s[0:1], s[2:3]
	s_cbranch_execnz .LBB0_147

.LBB0_133:
	s_waitcnt vmcnt(0)
	v_bfe_u32 v120, v12, 16, 1
	s_movk_i32 s2, 0x7fff
	v_add3_u32 v120, v12, v120, s2
	v_bfe_u32 v121, v13, 16, 1
	v_lshrrev_b32_e32 v120, 16, v120
	v_add3_u32 v121, v13, v121, s2
	s_mov_b32 s3, 0xffff0000
	v_and_or_b32 v120, v121, s3, v120
	v_bfe_u32 v121, v14, 16, 1
	v_add3_u32 v121, v14, v121, s2
	v_bfe_u32 v122, v15, 16, 1
	v_lshrrev_b32_e32 v121, 16, v121
	v_add3_u32 v122, v15, v122, s2
	v_and_or_b32 v121, v122, s3, v121
	v_bfe_u32 v122, v8, 16, 1
	v_add3_u32 v122, v8, v122, s2
	v_bfe_u32 v123, v9, 16, 1
	v_lshrrev_b32_e32 v122, 16, v122
	v_add3_u32 v123, v9, v123, s2
	v_and_or_b32 v122, v123, s3, v122
	v_bfe_u32 v123, v10, 16, 1
	v_add3_u32 v123, v10, v123, s2
	v_bfe_u32 v124, v11, 16, 1
	v_lshrrev_b32_e32 v123, 16, v123
	v_add3_u32 v124, v11, v124, s2
	v_and_or_b32 v123, v124, s3, v123
	v_lshl_add_u64 v[124:125], v[134:135], 4, s[34:35]
	global_store_dwordx4 v[124:125], v[120:123], off sc1
	s_or_b64 exec, exec, s[0:1]
	s_and_saveexec_b64 s[0:1], s[6:7]
	s_cbranch_execnz .LBB0_149

.LBB0_135:
	s_waitcnt vmcnt(0)
	v_bfe_u32 v120, v28, 16, 1
	s_movk_i32 s2, 0x7fff
	v_add3_u32 v120, v28, v120, s2
	v_bfe_u32 v121, v29, 16, 1
	v_lshrrev_b32_e32 v120, 16, v120
	v_add3_u32 v121, v29, v121, s2
	s_mov_b32 s3, 0xffff0000
	v_and_or_b32 v120, v121, s3, v120
	v_bfe_u32 v121, v30, 16, 1
	v_add3_u32 v121, v30, v121, s2
	v_bfe_u32 v122, v31, 16, 1
	v_lshrrev_b32_e32 v121, 16, v121
	v_add3_u32 v122, v31, v122, s2
	v_and_or_b32 v121, v122, s3, v121
	v_bfe_u32 v122, v24, 16, 1
	v_add3_u32 v122, v24, v122, s2
	v_bfe_u32 v123, v25, 16, 1
	v_lshrrev_b32_e32 v122, 16, v122
	v_add3_u32 v123, v25, v123, s2
	v_and_or_b32 v122, v123, s3, v122
	v_bfe_u32 v123, v26, 16, 1
	v_add3_u32 v123, v26, v123, s2
	v_bfe_u32 v124, v27, 16, 1
	v_lshrrev_b32_e32 v123, 16, v123
	v_add3_u32 v124, v27, v124, s2
	v_and_or_b32 v123, v124, s3, v123
	v_lshl_add_u64 v[124:125], v[138:139], 4, s[34:35]
	global_store_dwordx4 v[124:125], v[120:123], off sc1
	s_or_b64 exec, exec, s[0:1]
	s_and_saveexec_b64 s[0:1], s[10:11]
	s_cbranch_execnz .LBB0_151

.LBB0_137:
	s_waitcnt vmcnt(0)
	v_bfe_u32 v120, v44, 16, 1
	s_movk_i32 s2, 0x7fff
	v_add3_u32 v120, v44, v120, s2
	v_bfe_u32 v121, v45, 16, 1
	v_lshrrev_b32_e32 v120, 16, v120
	v_add3_u32 v121, v45, v121, s2
	s_mov_b32 s3, 0xffff0000
	v_and_or_b32 v120, v121, s3, v120
	v_bfe_u32 v121, v46, 16, 1
	v_add3_u32 v121, v46, v121, s2
	v_bfe_u32 v122, v47, 16, 1
	v_lshrrev_b32_e32 v121, 16, v121
	v_add3_u32 v122, v47, v122, s2
	v_and_or_b32 v121, v122, s3, v121
	v_bfe_u32 v122, v40, 16, 1
	v_add3_u32 v122, v40, v122, s2
	v_bfe_u32 v123, v41, 16, 1
	v_lshrrev_b32_e32 v122, 16, v122
	v_add3_u32 v123, v41, v123, s2
	v_and_or_b32 v122, v123, s3, v122
	v_bfe_u32 v123, v42, 16, 1
	v_add3_u32 v123, v42, v123, s2
	v_bfe_u32 v124, v43, 16, 1
	v_lshrrev_b32_e32 v123, 16, v123
	v_add3_u32 v124, v43, v124, s2
	v_and_or_b32 v123, v124, s3, v123
	v_lshl_add_u64 v[124:125], v[142:143], 4, s[34:35]
	global_store_dwordx4 v[124:125], v[120:123], off sc1
	s_or_b64 exec, exec, s[0:1]
	s_and_saveexec_b64 s[0:1], s[14:15]
	s_cbranch_execnz .LBB0_153

.LBB0_139:
	s_waitcnt vmcnt(0)
	v_bfe_u32 v120, v60, 16, 1
	s_movk_i32 s2, 0x7fff
	v_add3_u32 v120, v60, v120, s2
	v_bfe_u32 v121, v61, 16, 1
	v_lshrrev_b32_e32 v120, 16, v120
	v_add3_u32 v121, v61, v121, s2
	s_mov_b32 s3, 0xffff0000
	v_and_or_b32 v120, v121, s3, v120
	v_bfe_u32 v121, v62, 16, 1
	v_add3_u32 v121, v62, v121, s2
	v_bfe_u32 v122, v63, 16, 1
	v_lshrrev_b32_e32 v121, 16, v121
	v_add3_u32 v122, v63, v122, s2
	v_and_or_b32 v121, v122, s3, v121
	v_bfe_u32 v122, v56, 16, 1
	v_add3_u32 v122, v56, v122, s2
	v_bfe_u32 v123, v57, 16, 1
	v_lshrrev_b32_e32 v122, 16, v122
	v_add3_u32 v123, v57, v123, s2
	v_and_or_b32 v122, v123, s3, v122
	v_bfe_u32 v123, v58, 16, 1
	v_add3_u32 v123, v58, v123, s2
	v_bfe_u32 v124, v59, 16, 1
	v_lshrrev_b32_e32 v123, 16, v123
	v_add3_u32 v124, v59, v124, s2
	v_and_or_b32 v123, v124, s3, v123
	v_lshl_add_u64 v[124:125], v[146:147], 4, s[34:35]
	global_store_dwordx4 v[124:125], v[120:123], off sc1
	s_or_b64 exec, exec, s[0:1]
	s_and_saveexec_b64 s[0:1], s[18:19]
	s_cbranch_execnz .LBB0_155

.LBB0_141:
	s_waitcnt vmcnt(0)
	v_bfe_u32 v120, v76, 16, 1
	s_movk_i32 s2, 0x7fff
	v_add3_u32 v120, v76, v120, s2
	v_bfe_u32 v121, v77, 16, 1
	v_lshrrev_b32_e32 v120, 16, v120
	v_add3_u32 v121, v77, v121, s2
	s_mov_b32 s3, 0xffff0000
	v_and_or_b32 v120, v121, s3, v120
	v_bfe_u32 v121, v78, 16, 1
	v_add3_u32 v121, v78, v121, s2
	v_bfe_u32 v122, v79, 16, 1
	v_lshrrev_b32_e32 v121, 16, v121
	v_add3_u32 v122, v79, v122, s2
	v_and_or_b32 v121, v122, s3, v121
	v_bfe_u32 v122, v72, 16, 1
	v_add3_u32 v122, v72, v122, s2
	v_bfe_u32 v123, v73, 16, 1
	v_lshrrev_b32_e32 v122, 16, v122
	v_add3_u32 v123, v73, v123, s2
	v_and_or_b32 v122, v123, s3, v122
	v_bfe_u32 v123, v74, 16, 1
	v_add3_u32 v123, v74, v123, s2
	v_bfe_u32 v124, v75, 16, 1
	v_lshrrev_b32_e32 v123, 16, v123
	v_add3_u32 v124, v75, v124, s2
	v_and_or_b32 v123, v124, s3, v123
	v_lshl_add_u64 v[124:125], v[150:151], 4, s[34:35]
	global_store_dwordx4 v[124:125], v[120:123], off sc1
	s_or_b64 exec, exec, s[0:1]
	s_and_saveexec_b64 s[0:1], s[22:23]
	s_cbranch_execnz .LBB0_157

.LBB0_143:
	s_waitcnt vmcnt(0)
	v_bfe_u32 v120, v92, 16, 1
	s_movk_i32 s2, 0x7fff
	v_add3_u32 v120, v92, v120, s2
	v_bfe_u32 v121, v93, 16, 1
	v_lshrrev_b32_e32 v120, 16, v120
	v_add3_u32 v121, v93, v121, s2
	s_mov_b32 s3, 0xffff0000
	v_and_or_b32 v120, v121, s3, v120
	v_bfe_u32 v121, v94, 16, 1
	v_add3_u32 v121, v94, v121, s2
	v_bfe_u32 v122, v95, 16, 1
	v_lshrrev_b32_e32 v121, 16, v121
	v_add3_u32 v122, v95, v122, s2
	v_and_or_b32 v121, v122, s3, v121
	v_bfe_u32 v122, v88, 16, 1
	v_add3_u32 v122, v88, v122, s2
	v_bfe_u32 v123, v89, 16, 1
	v_lshrrev_b32_e32 v122, 16, v122
	v_add3_u32 v123, v89, v123, s2
	v_and_or_b32 v122, v123, s3, v122
	v_bfe_u32 v123, v90, 16, 1
	v_add3_u32 v123, v90, v123, s2
	v_bfe_u32 v124, v91, 16, 1
	v_lshrrev_b32_e32 v123, 16, v123
	v_add3_u32 v124, v91, v124, s2
	v_and_or_b32 v123, v124, s3, v123
	v_lshl_add_u64 v[124:125], v[154:155], 4, s[34:35]
	global_store_dwordx4 v[124:125], v[120:123], off sc1
	s_or_b64 exec, exec, s[0:1]
	s_and_saveexec_b64 s[0:1], s[26:27]
	s_cbranch_execnz .LBB0_159

.LBB0_145:
	s_waitcnt vmcnt(0)
	v_bfe_u32 v120, v108, 16, 1
	s_movk_i32 s2, 0x7fff
	v_add3_u32 v120, v108, v120, s2
	v_bfe_u32 v121, v109, 16, 1
	v_lshrrev_b32_e32 v120, 16, v120
	v_add3_u32 v121, v109, v121, s2
	s_mov_b32 s3, 0xffff0000
	v_and_or_b32 v120, v121, s3, v120
	v_bfe_u32 v121, v110, 16, 1
	v_add3_u32 v121, v110, v121, s2
	v_bfe_u32 v122, v111, 16, 1
	v_lshrrev_b32_e32 v121, 16, v121
	v_add3_u32 v122, v111, v122, s2
	v_and_or_b32 v121, v122, s3, v121
	v_bfe_u32 v122, v104, 16, 1
	v_add3_u32 v122, v104, v122, s2
	v_bfe_u32 v123, v105, 16, 1
	v_lshrrev_b32_e32 v122, 16, v122
	v_add3_u32 v123, v105, v123, s2
	v_and_or_b32 v122, v123, s3, v122
	v_bfe_u32 v123, v106, 16, 1
	v_add3_u32 v123, v106, v123, s2
	v_bfe_u32 v124, v107, 16, 1
	v_lshrrev_b32_e32 v123, 16, v123
	v_add3_u32 v124, v107, v124, s2
	v_and_or_b32 v123, v124, s3, v123
	v_lshl_add_u64 v[124:125], v[158:159], 4, s[34:35]
	global_store_dwordx4 v[124:125], v[120:123], off sc1
	s_or_b64 exec, exec, s[0:1]
	s_and_saveexec_b64 s[0:1], s[30:31]
	s_cbranch_execnz .LBB0_161
	s_branch .LBB0_162

.LBB0_147:
	s_waitcnt vmcnt(0)
	v_bfe_u32 v120, v4, 16, 1
	s_movk_i32 s2, 0x7fff
	v_add3_u32 v120, v4, v120, s2
	v_bfe_u32 v121, v5, 16, 1
	v_lshrrev_b32_e32 v120, 16, v120
	v_add3_u32 v121, v5, v121, s2
	s_mov_b32 s3, 0xffff0000
	v_and_or_b32 v120, v121, s3, v120
	v_bfe_u32 v121, v6, 16, 1
	v_add3_u32 v121, v6, v121, s2
	v_bfe_u32 v122, v7, 16, 1
	v_lshrrev_b32_e32 v121, 16, v121
	v_add3_u32 v122, v7, v122, s2
	v_and_or_b32 v121, v122, s3, v121
	v_bfe_u32 v122, v0, 16, 1
	v_add3_u32 v122, v0, v122, s2
	v_bfe_u32 v123, v1, 16, 1
	v_lshrrev_b32_e32 v122, 16, v122
	v_add3_u32 v123, v1, v123, s2
	v_and_or_b32 v122, v123, s3, v122
	v_bfe_u32 v123, v2, 16, 1
	v_add3_u32 v123, v2, v123, s2
	v_bfe_u32 v124, v3, 16, 1
	v_lshrrev_b32_e32 v123, 16, v123
	v_add3_u32 v124, v3, v124, s2
	v_and_or_b32 v123, v124, s3, v123
	v_lshl_add_u64 v[124:125], v[132:133], 4, s[34:35]
	global_store_dwordx4 v[124:125], v[120:123], off sc1
	s_or_b64 exec, exec, s[0:1]
	s_and_saveexec_b64 s[0:1], s[4:5]
	s_cbranch_execnz .LBB0_133

.LBB0_149:
	s_waitcnt vmcnt(0)
	v_bfe_u32 v120, v20, 16, 1
	s_movk_i32 s2, 0x7fff
	v_add3_u32 v120, v20, v120, s2
	v_bfe_u32 v121, v21, 16, 1
	v_lshrrev_b32_e32 v120, 16, v120
	v_add3_u32 v121, v21, v121, s2
	s_mov_b32 s3, 0xffff0000
	v_and_or_b32 v120, v121, s3, v120
	v_bfe_u32 v121, v22, 16, 1
	v_add3_u32 v121, v22, v121, s2
	v_bfe_u32 v122, v23, 16, 1
	v_lshrrev_b32_e32 v121, 16, v121
	v_add3_u32 v122, v23, v122, s2
	v_and_or_b32 v121, v122, s3, v121
	v_bfe_u32 v122, v16, 16, 1
	v_add3_u32 v122, v16, v122, s2
	v_bfe_u32 v123, v17, 16, 1
	v_lshrrev_b32_e32 v122, 16, v122
	v_add3_u32 v123, v17, v123, s2
	v_and_or_b32 v122, v123, s3, v122
	v_bfe_u32 v123, v18, 16, 1
	v_add3_u32 v123, v18, v123, s2
	v_bfe_u32 v124, v19, 16, 1
	v_lshrrev_b32_e32 v123, 16, v123
	v_add3_u32 v124, v19, v124, s2
	v_and_or_b32 v123, v124, s3, v123
	v_lshl_add_u64 v[124:125], v[136:137], 4, s[34:35]
	global_store_dwordx4 v[124:125], v[120:123], off sc1
	s_or_b64 exec, exec, s[0:1]
	s_and_saveexec_b64 s[0:1], s[8:9]
	s_cbranch_execnz .LBB0_135

.LBB0_151:
	s_waitcnt vmcnt(0)
	v_bfe_u32 v120, v36, 16, 1
	s_movk_i32 s2, 0x7fff
	v_add3_u32 v120, v36, v120, s2
	v_bfe_u32 v121, v37, 16, 1
	v_lshrrev_b32_e32 v120, 16, v120
	v_add3_u32 v121, v37, v121, s2
	s_mov_b32 s3, 0xffff0000
	v_and_or_b32 v120, v121, s3, v120
	v_bfe_u32 v121, v38, 16, 1
	v_add3_u32 v121, v38, v121, s2
	v_bfe_u32 v122, v39, 16, 1
	v_lshrrev_b32_e32 v121, 16, v121
	v_add3_u32 v122, v39, v122, s2
	v_and_or_b32 v121, v122, s3, v121
	v_bfe_u32 v122, v32, 16, 1
	v_add3_u32 v122, v32, v122, s2
	v_bfe_u32 v123, v33, 16, 1
	v_lshrrev_b32_e32 v122, 16, v122
	v_add3_u32 v123, v33, v123, s2
	v_and_or_b32 v122, v123, s3, v122
	v_bfe_u32 v123, v34, 16, 1
	v_add3_u32 v123, v34, v123, s2
	v_bfe_u32 v124, v35, 16, 1
	v_lshrrev_b32_e32 v123, 16, v123
	v_add3_u32 v124, v35, v124, s2
	v_and_or_b32 v123, v124, s3, v123
	v_lshl_add_u64 v[124:125], v[140:141], 4, s[34:35]
	global_store_dwordx4 v[124:125], v[120:123], off sc1
	s_or_b64 exec, exec, s[0:1]
	s_and_saveexec_b64 s[0:1], s[12:13]
	s_cbranch_execnz .LBB0_137

.LBB0_153:
	s_waitcnt vmcnt(0)
	v_bfe_u32 v120, v52, 16, 1
	s_movk_i32 s2, 0x7fff
	v_add3_u32 v120, v52, v120, s2
	v_bfe_u32 v121, v53, 16, 1
	v_lshrrev_b32_e32 v120, 16, v120
	v_add3_u32 v121, v53, v121, s2
	s_mov_b32 s3, 0xffff0000
	v_and_or_b32 v120, v121, s3, v120
	v_bfe_u32 v121, v54, 16, 1
	v_add3_u32 v121, v54, v121, s2
	v_bfe_u32 v122, v55, 16, 1
	v_lshrrev_b32_e32 v121, 16, v121
	v_add3_u32 v122, v55, v122, s2
	v_and_or_b32 v121, v122, s3, v121
	v_bfe_u32 v122, v48, 16, 1
	v_add3_u32 v122, v48, v122, s2
	v_bfe_u32 v123, v49, 16, 1
	v_lshrrev_b32_e32 v122, 16, v122
	v_add3_u32 v123, v49, v123, s2
	v_and_or_b32 v122, v123, s3, v122
	v_bfe_u32 v123, v50, 16, 1
	v_add3_u32 v123, v50, v123, s2
	v_bfe_u32 v124, v51, 16, 1
	v_lshrrev_b32_e32 v123, 16, v123
	v_add3_u32 v124, v51, v124, s2
	v_and_or_b32 v123, v124, s3, v123
	v_lshl_add_u64 v[124:125], v[144:145], 4, s[34:35]
	global_store_dwordx4 v[124:125], v[120:123], off sc1
	s_or_b64 exec, exec, s[0:1]
	s_and_saveexec_b64 s[0:1], s[16:17]
	s_cbranch_execnz .LBB0_139

.LBB0_155:
	s_waitcnt vmcnt(0)
	v_bfe_u32 v120, v68, 16, 1
	s_movk_i32 s2, 0x7fff
	v_add3_u32 v120, v68, v120, s2
	v_bfe_u32 v121, v69, 16, 1
	v_lshrrev_b32_e32 v120, 16, v120
	v_add3_u32 v121, v69, v121, s2
	s_mov_b32 s3, 0xffff0000
	v_and_or_b32 v120, v121, s3, v120
	v_bfe_u32 v121, v70, 16, 1
	v_add3_u32 v121, v70, v121, s2
	v_bfe_u32 v122, v71, 16, 1
	v_lshrrev_b32_e32 v121, 16, v121
	v_add3_u32 v122, v71, v122, s2
	v_and_or_b32 v121, v122, s3, v121
	v_bfe_u32 v122, v64, 16, 1
	v_add3_u32 v122, v64, v122, s2
	v_bfe_u32 v123, v65, 16, 1
	v_lshrrev_b32_e32 v122, 16, v122
	v_add3_u32 v123, v65, v123, s2
	v_and_or_b32 v122, v123, s3, v122
	v_bfe_u32 v123, v66, 16, 1
	v_add3_u32 v123, v66, v123, s2
	v_bfe_u32 v124, v67, 16, 1
	v_lshrrev_b32_e32 v123, 16, v123
	v_add3_u32 v124, v67, v124, s2
	v_and_or_b32 v123, v124, s3, v123
	v_lshl_add_u64 v[124:125], v[148:149], 4, s[34:35]
	global_store_dwordx4 v[124:125], v[120:123], off sc1
	s_or_b64 exec, exec, s[0:1]
	s_and_saveexec_b64 s[0:1], s[20:21]
	s_cbranch_execnz .LBB0_141

.LBB0_157:
	s_waitcnt vmcnt(0)
	v_bfe_u32 v120, v84, 16, 1
	s_movk_i32 s2, 0x7fff
	v_add3_u32 v120, v84, v120, s2
	v_bfe_u32 v121, v85, 16, 1
	v_lshrrev_b32_e32 v120, 16, v120
	v_add3_u32 v121, v85, v121, s2
	s_mov_b32 s3, 0xffff0000
	v_and_or_b32 v120, v121, s3, v120
	v_bfe_u32 v121, v86, 16, 1
	v_add3_u32 v121, v86, v121, s2
	v_bfe_u32 v122, v87, 16, 1
	v_lshrrev_b32_e32 v121, 16, v121
	v_add3_u32 v122, v87, v122, s2
	v_and_or_b32 v121, v122, s3, v121
	v_bfe_u32 v122, v80, 16, 1
	v_add3_u32 v122, v80, v122, s2
	v_bfe_u32 v123, v81, 16, 1
	v_lshrrev_b32_e32 v122, 16, v122
	v_add3_u32 v123, v81, v123, s2
	v_and_or_b32 v122, v123, s3, v122
	v_bfe_u32 v123, v82, 16, 1
	v_add3_u32 v123, v82, v123, s2
	v_bfe_u32 v124, v83, 16, 1
	v_lshrrev_b32_e32 v123, 16, v123
	v_add3_u32 v124, v83, v124, s2
	v_and_or_b32 v123, v124, s3, v123
	v_lshl_add_u64 v[124:125], v[152:153], 4, s[34:35]
	global_store_dwordx4 v[124:125], v[120:123], off sc1
	s_or_b64 exec, exec, s[0:1]
	s_and_saveexec_b64 s[0:1], s[24:25]
	s_cbranch_execnz .LBB0_143

.LBB0_159:
	s_waitcnt vmcnt(0)
	v_bfe_u32 v120, v100, 16, 1
	s_movk_i32 s2, 0x7fff
	v_add3_u32 v120, v100, v120, s2
	v_bfe_u32 v121, v101, 16, 1
	v_lshrrev_b32_e32 v120, 16, v120
	v_add3_u32 v121, v101, v121, s2
	s_mov_b32 s3, 0xffff0000
	v_and_or_b32 v120, v121, s3, v120
	v_bfe_u32 v121, v102, 16, 1
	v_add3_u32 v121, v102, v121, s2
	v_bfe_u32 v122, v103, 16, 1
	v_lshrrev_b32_e32 v121, 16, v121
	v_add3_u32 v122, v103, v122, s2
	v_and_or_b32 v121, v122, s3, v121
	v_bfe_u32 v122, v96, 16, 1
	v_add3_u32 v122, v96, v122, s2
	v_bfe_u32 v123, v97, 16, 1
	v_lshrrev_b32_e32 v122, 16, v122
	v_add3_u32 v123, v97, v123, s2
	v_and_or_b32 v122, v123, s3, v122
	v_bfe_u32 v123, v98, 16, 1
	v_add3_u32 v123, v98, v123, s2
	v_bfe_u32 v124, v99, 16, 1
	v_lshrrev_b32_e32 v123, 16, v123
	v_add3_u32 v124, v99, v124, s2
	v_and_or_b32 v123, v124, s3, v123
	v_lshl_add_u64 v[124:125], v[156:157], 4, s[34:35]
	global_store_dwordx4 v[124:125], v[120:123], off sc1
	s_or_b64 exec, exec, s[0:1]
	s_and_saveexec_b64 s[0:1], s[28:29]
	s_cbranch_execnz .LBB0_145

.LBB0_161:
	s_waitcnt vmcnt(0)
	v_bfe_u32 v120, v116, 16, 1
	s_movk_i32 s2, 0x7fff
	v_add3_u32 v120, v116, v120, s2
	v_bfe_u32 v121, v117, 16, 1
	v_lshrrev_b32_e32 v120, 16, v120
	v_add3_u32 v121, v117, v121, s2
	s_mov_b32 s3, 0xffff0000
	v_and_or_b32 v120, v121, s3, v120
	v_bfe_u32 v121, v118, 16, 1
	v_add3_u32 v121, v118, v121, s2
	v_bfe_u32 v122, v119, 16, 1
	v_lshrrev_b32_e32 v121, 16, v121
	v_add3_u32 v122, v119, v122, s2
	v_and_or_b32 v121, v122, s3, v121
	v_bfe_u32 v122, v112, 16, 1
	v_add3_u32 v122, v112, v122, s2
	v_bfe_u32 v123, v113, 16, 1
	v_lshrrev_b32_e32 v122, 16, v122
	v_add3_u32 v123, v113, v123, s2
	v_and_or_b32 v122, v123, s3, v122
	v_bfe_u32 v123, v114, 16, 1
	v_add3_u32 v123, v114, v123, s2
	v_bfe_u32 v124, v115, 16, 1
	v_lshrrev_b32_e32 v123, 16, v123
	v_add3_u32 v124, v115, v124, s2
	v_and_or_b32 v123, v124, s3, v123
	v_lshl_add_u64 v[124:125], v[160:161], 4, s[34:35]
	global_store_dwordx4 v[124:125], v[120:123], off sc1

.LBB0_195:
	s_or_b64 exec, exec, s[84:85]
	s_waitcnt vmcnt(0)
	v_bfe_u32 v226, v124, 16, 1
	v_add3_u32 v124, v124, v226, s33
	v_bfe_u32 v226, v125, 16, 1
	v_lshrrev_b32_e32 v124, 16, v124
	v_add3_u32 v125, v125, v226, s33
	v_and_or_b32 v124, v125, s86, v124
	v_bfe_u32 v125, v126, 16, 1
	v_add3_u32 v125, v126, v125, s33
	v_bfe_u32 v126, v127, 16, 1
	v_lshrrev_b32_e32 v125, 16, v125
	v_add3_u32 v126, v127, v126, s33
	v_and_or_b32 v125, v126, s86, v125
	v_bfe_u32 v126, v120, 16, 1
	v_add3_u32 v120, v120, v126, s33
	v_bfe_u32 v126, v121, 16, 1
	v_lshrrev_b32_e32 v120, 16, v120
	v_add3_u32 v121, v121, v126, s33
	v_and_or_b32 v126, v121, s86, v120
	v_bfe_u32 v120, v122, 16, 1
	v_add3_u32 v120, v122, v120, s33
	v_bfe_u32 v121, v123, 16, 1
	v_lshrrev_b32_e32 v120, 16, v120
	v_add3_u32 v121, v123, v121, s33
	v_and_or_b32 v127, v121, s86, v120
	v_lshl_add_u64 v[120:121], s[38:39], 0, v[130:131]
	global_store_dwordx4 v[120:121], v[124:127], off sc1
	s_and_saveexec_b64 s[28:29], s[26:27]
	s_cbranch_execz .LBB0_210
	v_bfe_u32 v120, v4, 16, 1
	v_add3_u32 v120, v4, v120, s33
	v_bfe_u32 v121, v5, 16, 1
	v_lshrrev_b32_e32 v120, 16, v120
	v_add3_u32 v121, v5, v121, s33
	v_and_or_b32 v120, v121, s86, v120
	v_bfe_u32 v121, v6, 16, 1
	v_add3_u32 v121, v6, v121, s33
	v_bfe_u32 v122, v7, 16, 1
	v_lshrrev_b32_e32 v121, 16, v121
	v_add3_u32 v122, v7, v122, s33
	v_and_or_b32 v121, v122, s86, v121
	v_bfe_u32 v122, v0, 16, 1
	v_add3_u32 v122, v0, v122, s33
	v_bfe_u32 v123, v1, 16, 1
	v_lshrrev_b32_e32 v122, 16, v122
	v_add3_u32 v123, v1, v123, s33
	v_and_or_b32 v122, v123, s86, v122
	v_bfe_u32 v123, v2, 16, 1
	v_add3_u32 v123, v2, v123, s33
	v_bfe_u32 v124, v3, 16, 1
	v_lshrrev_b32_e32 v123, 16, v123
	v_add3_u32 v124, v3, v124, s33
	v_and_or_b32 v123, v124, s86, v123
	v_lshl_add_u64 v[124:125], s[38:39], 0, v[220:221]
	global_store_dwordx4 v[124:125], v[120:123], off sc1
	s_or_b64 exec, exec, s[28:29]
	s_and_saveexec_b64 s[26:27], s[24:25]
	s_cbranch_execnz .LBB0_211

.LBB0_198:
	v_bfe_u32 v120, v20, 16, 1
	v_add3_u32 v120, v20, v120, s33
	v_bfe_u32 v121, v21, 16, 1
	v_lshrrev_b32_e32 v120, 16, v120
	v_add3_u32 v121, v21, v121, s33
	v_and_or_b32 v120, v121, s86, v120
	v_bfe_u32 v121, v22, 16, 1
	v_add3_u32 v121, v22, v121, s33
	v_bfe_u32 v122, v23, 16, 1
	v_lshrrev_b32_e32 v121, 16, v121
	v_add3_u32 v122, v23, v122, s33
	v_and_or_b32 v121, v122, s86, v121
	v_bfe_u32 v122, v16, 16, 1
	v_add3_u32 v122, v16, v122, s33
	v_bfe_u32 v123, v17, 16, 1
	v_lshrrev_b32_e32 v122, 16, v122
	v_add3_u32 v123, v17, v123, s33
	v_and_or_b32 v122, v123, s86, v122
	v_bfe_u32 v123, v18, 16, 1
	v_add3_u32 v123, v18, v123, s33
	v_bfe_u32 v124, v19, 16, 1
	v_lshrrev_b32_e32 v123, 16, v123
	v_add3_u32 v124, v19, v124, s33
	v_and_or_b32 v123, v124, s86, v123
	v_lshl_add_u64 v[124:125], s[38:39], 0, v[146:147]
	global_store_dwordx4 v[124:125], v[120:123], off sc1
	s_or_b64 exec, exec, s[24:25]
	s_and_saveexec_b64 s[22:23], s[20:21]
	s_cbranch_execnz .LBB0_213

.LBB0_200:
	v_bfe_u32 v120, v36, 16, 1
	v_add3_u32 v120, v36, v120, s33
	v_bfe_u32 v121, v37, 16, 1
	v_lshrrev_b32_e32 v120, 16, v120
	v_add3_u32 v121, v37, v121, s33
	v_and_or_b32 v120, v121, s86, v120
	v_bfe_u32 v121, v38, 16, 1
	v_add3_u32 v121, v38, v121, s33
	v_bfe_u32 v122, v39, 16, 1
	v_lshrrev_b32_e32 v121, 16, v121
	v_add3_u32 v122, v39, v122, s33
	v_and_or_b32 v121, v122, s86, v121
	v_bfe_u32 v122, v32, 16, 1
	v_add3_u32 v122, v32, v122, s33
	v_bfe_u32 v123, v33, 16, 1
	v_lshrrev_b32_e32 v122, 16, v122
	v_add3_u32 v123, v33, v123, s33
	v_and_or_b32 v122, v123, s86, v122
	v_bfe_u32 v123, v34, 16, 1
	v_add3_u32 v123, v34, v123, s33
	v_bfe_u32 v124, v35, 16, 1
	v_lshrrev_b32_e32 v123, 16, v123
	v_add3_u32 v124, v35, v124, s33
	v_and_or_b32 v123, v124, s86, v123
	v_lshl_add_u64 v[124:125], s[38:39], 0, v[158:159]
	global_store_dwordx4 v[124:125], v[120:123], off sc1
	s_or_b64 exec, exec, s[20:21]
	s_and_saveexec_b64 s[18:19], s[16:17]
	s_cbranch_execnz .LBB0_215

.LBB0_202:
	v_bfe_u32 v120, v52, 16, 1
	v_add3_u32 v120, v52, v120, s33
	v_bfe_u32 v121, v53, 16, 1
	v_lshrrev_b32_e32 v120, 16, v120
	v_add3_u32 v121, v53, v121, s33
	v_and_or_b32 v120, v121, s86, v120
	v_bfe_u32 v121, v54, 16, 1
	v_add3_u32 v121, v54, v121, s33
	v_bfe_u32 v122, v55, 16, 1
	v_lshrrev_b32_e32 v121, 16, v121
	v_add3_u32 v122, v55, v122, s33
	v_and_or_b32 v121, v122, s86, v121
	v_bfe_u32 v122, v48, 16, 1
	v_add3_u32 v122, v48, v122, s33
	v_bfe_u32 v123, v49, 16, 1
	v_lshrrev_b32_e32 v122, 16, v122
	v_add3_u32 v123, v49, v123, s33
	v_and_or_b32 v122, v123, s86, v122
	v_bfe_u32 v123, v50, 16, 1
	v_add3_u32 v123, v50, v123, s33
	v_bfe_u32 v124, v51, 16, 1
	v_lshrrev_b32_e32 v123, 16, v123
	v_add3_u32 v124, v51, v124, s33
	v_and_or_b32 v123, v124, s86, v123
	v_lshl_add_u64 v[124:125], s[38:39], 0, v[170:171]
	global_store_dwordx4 v[124:125], v[120:123], off sc1
	s_or_b64 exec, exec, s[16:17]
	s_and_saveexec_b64 s[14:15], s[12:13]
	s_cbranch_execnz .LBB0_217

.LBB0_204:
	v_bfe_u32 v120, v68, 16, 1
	v_add3_u32 v120, v68, v120, s33
	v_bfe_u32 v121, v69, 16, 1
	v_lshrrev_b32_e32 v120, 16, v120
	v_add3_u32 v121, v69, v121, s33
	v_and_or_b32 v120, v121, s86, v120
	v_bfe_u32 v121, v70, 16, 1
	v_add3_u32 v121, v70, v121, s33
	v_bfe_u32 v122, v71, 16, 1
	v_lshrrev_b32_e32 v121, 16, v121
	v_add3_u32 v122, v71, v122, s33
	v_and_or_b32 v121, v122, s86, v121
	v_bfe_u32 v122, v64, 16, 1
	v_add3_u32 v122, v64, v122, s33
	v_bfe_u32 v123, v65, 16, 1
	v_lshrrev_b32_e32 v122, 16, v122
	v_add3_u32 v123, v65, v123, s33
	v_and_or_b32 v122, v123, s86, v122
	v_bfe_u32 v123, v66, 16, 1
	v_add3_u32 v123, v66, v123, s33
	v_bfe_u32 v124, v67, 16, 1
	v_lshrrev_b32_e32 v123, 16, v123
	v_add3_u32 v124, v67, v124, s33
	v_and_or_b32 v123, v124, s86, v123
	v_lshl_add_u64 v[124:125], s[38:39], 0, v[182:183]
	global_store_dwordx4 v[124:125], v[120:123], off sc1
	s_or_b64 exec, exec, s[12:13]
	s_and_saveexec_b64 s[10:11], s[8:9]
	s_cbranch_execnz .LBB0_219

.LBB0_206:
	v_bfe_u32 v120, v84, 16, 1
	v_add3_u32 v120, v84, v120, s33
	v_bfe_u32 v121, v85, 16, 1
	v_lshrrev_b32_e32 v120, 16, v120
	v_add3_u32 v121, v85, v121, s33
	v_and_or_b32 v120, v121, s86, v120
	v_bfe_u32 v121, v86, 16, 1
	v_add3_u32 v121, v86, v121, s33
	v_bfe_u32 v122, v87, 16, 1
	v_lshrrev_b32_e32 v121, 16, v121
	v_add3_u32 v122, v87, v122, s33
	v_and_or_b32 v121, v122, s86, v121
	v_bfe_u32 v122, v80, 16, 1
	v_add3_u32 v122, v80, v122, s33
	v_bfe_u32 v123, v81, 16, 1
	v_lshrrev_b32_e32 v122, 16, v122
	v_add3_u32 v123, v81, v123, s33
	v_and_or_b32 v122, v123, s86, v122
	v_bfe_u32 v123, v82, 16, 1
	v_add3_u32 v123, v82, v123, s33
	v_bfe_u32 v124, v83, 16, 1
	v_lshrrev_b32_e32 v123, 16, v123
	v_add3_u32 v124, v83, v124, s33
	v_and_or_b32 v123, v124, s86, v123
	v_lshl_add_u64 v[124:125], s[38:39], 0, v[194:195]
	global_store_dwordx4 v[124:125], v[120:123], off sc1
	s_or_b64 exec, exec, s[8:9]
	s_and_saveexec_b64 s[6:7], s[4:5]
	s_cbranch_execnz .LBB0_221

.LBB0_208:
	v_bfe_u32 v120, v100, 16, 1
	v_add3_u32 v120, v100, v120, s33
	v_bfe_u32 v121, v101, 16, 1
	v_lshrrev_b32_e32 v120, 16, v120
	v_add3_u32 v121, v101, v121, s33
	v_and_or_b32 v120, v121, s86, v120
	v_bfe_u32 v121, v102, 16, 1
	v_add3_u32 v121, v102, v121, s33
	v_bfe_u32 v122, v103, 16, 1
	v_lshrrev_b32_e32 v121, 16, v121
	v_add3_u32 v122, v103, v122, s33
	v_and_or_b32 v121, v122, s86, v121
	v_bfe_u32 v122, v96, 16, 1
	v_add3_u32 v122, v96, v122, s33
	v_bfe_u32 v123, v97, 16, 1
	v_lshrrev_b32_e32 v122, 16, v122
	v_add3_u32 v123, v97, v123, s33
	v_and_or_b32 v122, v123, s86, v122
	v_bfe_u32 v123, v98, 16, 1
	v_add3_u32 v123, v98, v123, s33
	v_bfe_u32 v124, v99, 16, 1
	v_lshrrev_b32_e32 v123, 16, v123
	v_add3_u32 v124, v99, v124, s33
	v_and_or_b32 v123, v124, s86, v123
	v_lshl_add_u64 v[124:125], s[38:39], 0, v[206:207]
	global_store_dwordx4 v[124:125], v[120:123], off sc1
	s_or_b64 exec, exec, s[4:5]
	s_and_saveexec_b64 s[2:3], s[0:1]
	s_cbranch_execnz .LBB0_223

.LBB0_211:
	v_bfe_u32 v120, v12, 16, 1
	v_add3_u32 v120, v12, v120, s33
	v_bfe_u32 v121, v13, 16, 1
	v_lshrrev_b32_e32 v120, 16, v120
	v_add3_u32 v121, v13, v121, s33
	v_and_or_b32 v120, v121, s86, v120
	v_bfe_u32 v121, v14, 16, 1
	v_add3_u32 v121, v14, v121, s33
	v_bfe_u32 v122, v15, 16, 1
	v_lshrrev_b32_e32 v121, 16, v121
	v_add3_u32 v122, v15, v122, s33
	v_and_or_b32 v121, v122, s86, v121
	v_bfe_u32 v122, v8, 16, 1
	v_add3_u32 v122, v8, v122, s33
	v_bfe_u32 v123, v9, 16, 1
	v_lshrrev_b32_e32 v122, 16, v122
	v_add3_u32 v123, v9, v123, s33
	v_and_or_b32 v122, v123, s86, v122
	v_bfe_u32 v123, v10, 16, 1
	v_add3_u32 v123, v10, v123, s33
	v_bfe_u32 v124, v11, 16, 1
	v_lshrrev_b32_e32 v123, 16, v123
	v_add3_u32 v124, v11, v124, s33
	v_and_or_b32 v123, v124, s86, v123
	v_lshl_add_u64 v[124:125], s[38:39], 0, v[140:141]
	global_store_dwordx4 v[124:125], v[120:123], off sc1
	s_or_b64 exec, exec, s[26:27]
	s_and_saveexec_b64 s[24:25], s[22:23]
	s_cbranch_execnz .LBB0_198

.LBB0_213:
	v_bfe_u32 v120, v28, 16, 1
	v_add3_u32 v120, v28, v120, s33
	v_bfe_u32 v121, v29, 16, 1
	v_lshrrev_b32_e32 v120, 16, v120
	v_add3_u32 v121, v29, v121, s33
	v_and_or_b32 v120, v121, s86, v120
	v_bfe_u32 v121, v30, 16, 1
	v_add3_u32 v121, v30, v121, s33
	v_bfe_u32 v122, v31, 16, 1
	v_lshrrev_b32_e32 v121, 16, v121
	v_add3_u32 v122, v31, v122, s33
	v_and_or_b32 v121, v122, s86, v121
	v_bfe_u32 v122, v24, 16, 1
	v_add3_u32 v122, v24, v122, s33
	v_bfe_u32 v123, v25, 16, 1
	v_lshrrev_b32_e32 v122, 16, v122
	v_add3_u32 v123, v25, v123, s33
	v_and_or_b32 v122, v123, s86, v122
	v_bfe_u32 v123, v26, 16, 1
	v_add3_u32 v123, v26, v123, s33
	v_bfe_u32 v124, v27, 16, 1
	v_lshrrev_b32_e32 v123, 16, v123
	v_add3_u32 v124, v27, v124, s33
	v_and_or_b32 v123, v124, s86, v123
	v_lshl_add_u64 v[124:125], s[38:39], 0, v[152:153]
	global_store_dwordx4 v[124:125], v[120:123], off sc1
	s_or_b64 exec, exec, s[22:23]
	s_and_saveexec_b64 s[20:21], s[18:19]
	s_cbranch_execnz .LBB0_200

.LBB0_215:
	v_bfe_u32 v120, v44, 16, 1
	v_add3_u32 v120, v44, v120, s33
	v_bfe_u32 v121, v45, 16, 1
	v_lshrrev_b32_e32 v120, 16, v120
	v_add3_u32 v121, v45, v121, s33
	v_and_or_b32 v120, v121, s86, v120
	v_bfe_u32 v121, v46, 16, 1
	v_add3_u32 v121, v46, v121, s33
	v_bfe_u32 v122, v47, 16, 1
	v_lshrrev_b32_e32 v121, 16, v121
	v_add3_u32 v122, v47, v122, s33
	v_and_or_b32 v121, v122, s86, v121
	v_bfe_u32 v122, v40, 16, 1
	v_add3_u32 v122, v40, v122, s33
	v_bfe_u32 v123, v41, 16, 1
	v_lshrrev_b32_e32 v122, 16, v122
	v_add3_u32 v123, v41, v123, s33
	v_and_or_b32 v122, v123, s86, v122
	v_bfe_u32 v123, v42, 16, 1
	v_add3_u32 v123, v42, v123, s33
	v_bfe_u32 v124, v43, 16, 1
	v_lshrrev_b32_e32 v123, 16, v123
	v_add3_u32 v124, v43, v124, s33
	v_and_or_b32 v123, v124, s86, v123
	v_lshl_add_u64 v[124:125], s[38:39], 0, v[164:165]
	global_store_dwordx4 v[124:125], v[120:123], off sc1
	s_or_b64 exec, exec, s[18:19]
	s_and_saveexec_b64 s[16:17], s[14:15]
	s_cbranch_execnz .LBB0_202

.LBB0_217:
	v_bfe_u32 v120, v60, 16, 1
	v_add3_u32 v120, v60, v120, s33
	v_bfe_u32 v121, v61, 16, 1
	v_lshrrev_b32_e32 v120, 16, v120
	v_add3_u32 v121, v61, v121, s33
	v_and_or_b32 v120, v121, s86, v120
	v_bfe_u32 v121, v62, 16, 1
	v_add3_u32 v121, v62, v121, s33
	v_bfe_u32 v122, v63, 16, 1
	v_lshrrev_b32_e32 v121, 16, v121
	v_add3_u32 v122, v63, v122, s33
	v_and_or_b32 v121, v122, s86, v121
	v_bfe_u32 v122, v56, 16, 1
	v_add3_u32 v122, v56, v122, s33
	v_bfe_u32 v123, v57, 16, 1
	v_lshrrev_b32_e32 v122, 16, v122
	v_add3_u32 v123, v57, v123, s33
	v_and_or_b32 v122, v123, s86, v122
	v_bfe_u32 v123, v58, 16, 1
	v_add3_u32 v123, v58, v123, s33
	v_bfe_u32 v124, v59, 16, 1
	v_lshrrev_b32_e32 v123, 16, v123
	v_add3_u32 v124, v59, v124, s33
	v_and_or_b32 v123, v124, s86, v123
	v_lshl_add_u64 v[124:125], s[38:39], 0, v[176:177]
	global_store_dwordx4 v[124:125], v[120:123], off sc1
	s_or_b64 exec, exec, s[14:15]
	s_and_saveexec_b64 s[12:13], s[10:11]
	s_cbranch_execnz .LBB0_204

.LBB0_219:
	v_bfe_u32 v120, v76, 16, 1
	v_add3_u32 v120, v76, v120, s33
	v_bfe_u32 v121, v77, 16, 1
	v_lshrrev_b32_e32 v120, 16, v120
	v_add3_u32 v121, v77, v121, s33
	v_and_or_b32 v120, v121, s86, v120
	v_bfe_u32 v121, v78, 16, 1
	v_add3_u32 v121, v78, v121, s33
	v_bfe_u32 v122, v79, 16, 1
	v_lshrrev_b32_e32 v121, 16, v121
	v_add3_u32 v122, v79, v122, s33
	v_and_or_b32 v121, v122, s86, v121
	v_bfe_u32 v122, v72, 16, 1
	v_add3_u32 v122, v72, v122, s33
	v_bfe_u32 v123, v73, 16, 1
	v_lshrrev_b32_e32 v122, 16, v122
	v_add3_u32 v123, v73, v123, s33
	v_and_or_b32 v122, v123, s86, v122
	v_bfe_u32 v123, v74, 16, 1
	v_add3_u32 v123, v74, v123, s33
	v_bfe_u32 v124, v75, 16, 1
	v_lshrrev_b32_e32 v123, 16, v123
	v_add3_u32 v124, v75, v124, s33
	v_and_or_b32 v123, v124, s86, v123
	v_lshl_add_u64 v[124:125], s[38:39], 0, v[188:189]
	global_store_dwordx4 v[124:125], v[120:123], off sc1
	s_or_b64 exec, exec, s[10:11]
	s_and_saveexec_b64 s[8:9], s[6:7]
	s_cbranch_execnz .LBB0_206

.LBB0_221:
	v_bfe_u32 v120, v92, 16, 1
	v_add3_u32 v120, v92, v120, s33
	v_bfe_u32 v121, v93, 16, 1
	v_lshrrev_b32_e32 v120, 16, v120
	v_add3_u32 v121, v93, v121, s33
	v_and_or_b32 v120, v121, s86, v120
	v_bfe_u32 v121, v94, 16, 1
	v_add3_u32 v121, v94, v121, s33
	v_bfe_u32 v122, v95, 16, 1
	v_lshrrev_b32_e32 v121, 16, v121
	v_add3_u32 v122, v95, v122, s33
	v_and_or_b32 v121, v122, s86, v121
	v_bfe_u32 v122, v88, 16, 1
	v_add3_u32 v122, v88, v122, s33
	v_bfe_u32 v123, v89, 16, 1
	v_lshrrev_b32_e32 v122, 16, v122
	v_add3_u32 v123, v89, v123, s33
	v_and_or_b32 v122, v123, s86, v122
	v_bfe_u32 v123, v90, 16, 1
	v_add3_u32 v123, v90, v123, s33
	v_bfe_u32 v124, v91, 16, 1
	v_lshrrev_b32_e32 v123, 16, v123
	v_add3_u32 v124, v91, v124, s33
	v_and_or_b32 v123, v124, s86, v123
	v_lshl_add_u64 v[124:125], s[38:39], 0, v[200:201]
	global_store_dwordx4 v[124:125], v[120:123], off sc1
	s_or_b64 exec, exec, s[6:7]
	s_and_saveexec_b64 s[4:5], s[2:3]
	s_cbranch_execnz .LBB0_208

.LBB0_223:
	v_bfe_u32 v120, v108, 16, 1
	v_add3_u32 v120, v108, v120, s33
	v_bfe_u32 v121, v109, 16, 1
	v_lshrrev_b32_e32 v120, 16, v120
	v_add3_u32 v121, v109, v121, s33
	v_and_or_b32 v120, v121, s86, v120
	v_bfe_u32 v121, v110, 16, 1
	v_add3_u32 v121, v110, v121, s33
	v_bfe_u32 v122, v111, 16, 1
	v_lshrrev_b32_e32 v121, 16, v121
	v_add3_u32 v122, v111, v122, s33
	v_and_or_b32 v121, v122, s86, v121
	v_bfe_u32 v122, v104, 16, 1
	v_add3_u32 v122, v104, v122, s33
	v_bfe_u32 v123, v105, 16, 1
	v_lshrrev_b32_e32 v122, 16, v122
	v_add3_u32 v123, v105, v123, s33
	v_and_or_b32 v122, v123, s86, v122
	v_bfe_u32 v123, v106, 16, 1
	v_add3_u32 v123, v106, v123, s33
	v_bfe_u32 v124, v107, 16, 1
	v_lshrrev_b32_e32 v123, 16, v123
	v_add3_u32 v124, v107, v124, s33
	v_and_or_b32 v123, v124, s86, v123
	v_lshl_add_u64 v[124:125], s[38:39], 0, v[212:213]
	global_store_dwordx4 v[124:125], v[120:123], off sc1
	s_or_b64 exec, exec, s[2:3]
	s_and_saveexec_b64 s[0:1], vcc
	s_cbranch_execz .LBB0_164
.LBB0_224:
	v_bfe_u32 v120, v116, 16, 1
	v_add3_u32 v120, v116, v120, s33
	v_bfe_u32 v121, v117, 16, 1
	v_lshrrev_b32_e32 v120, 16, v120
	v_add3_u32 v121, v117, v121, s33
	v_and_or_b32 v120, v121, s86, v120
	v_bfe_u32 v121, v118, 16, 1
	v_add3_u32 v121, v118, v121, s33
	v_bfe_u32 v122, v119, 16, 1
	v_lshrrev_b32_e32 v121, 16, v121
	v_add3_u32 v122, v119, v122, s33
	v_and_or_b32 v121, v122, s86, v121
	v_bfe_u32 v122, v112, 16, 1
	v_add3_u32 v122, v112, v122, s33
	v_bfe_u32 v123, v113, 16, 1
	v_lshrrev_b32_e32 v122, 16, v122
	v_add3_u32 v123, v113, v123, s33
	v_and_or_b32 v122, v123, s86, v122
	v_bfe_u32 v123, v114, 16, 1
	v_add3_u32 v123, v114, v123, s33
	v_bfe_u32 v124, v115, 16, 1
	v_lshrrev_b32_e32 v123, 16, v123
	v_add3_u32 v124, v115, v124, s33
	v_and_or_b32 v123, v124, s86, v123
	v_lshl_add_u64 v[124:125], s[38:39], 0, v[218:219]
	global_store_dwordx4 v[124:125], v[120:123], off sc1
	s_branch .LBB0_164
